# nt (streaming) cache policy on once-read f32 streams: weight elements in all transposes, w_ada, x in the norm
# speedup vs baseline: 1.0331x; 1.0298x over previous
; #define LAS __attribute__((address_space(3)))
; __device__ __forceinline__ void transpose_item(const float* W, int K, int N, bf16* WT, int mode, LAS float* scr, int item, int lane) { transpose_item_t<false>(W, K, N, WT, mode, scr, item, lane, nullptr, nullptr, nullptr, nullptr); }
; template <bool SCALED> __device__ __forceinline__ void transpose_item_t(const float* W, int K, int N, bf16* WT, int mode, LAS float* scr, int item, int lane, const float* gvec, const float* scv, const float* shv, float* biasp) {
;     const int nblk = N / 32, kb = item / nblk, nb = item % nblk, k0 = 64 * kb, n0 = 32 * nb, d0 = dst_row0(mode, n0);
;     float tv[32];
; #pragma unroll
;     for (int i = 0; i < 32; ++i) tv[i] = W[(size_t)(k0 + 2 * i + (lane >> 5)) * N + n0 + (lane & 31)];
; __global__ void __launch_bounds__(512, 2) hybrid_fwd(Args args) {
;     ...
;             transpose_item(w_o, DM, DM, WO, 0, scr, r, lane);
.LBB0_29:
	s_cmpk_gt_i32 s16, 0xaff
	s_mov_b64 s[4:5], -1
	s_cbranch_scc0 .LBB0_43
	s_cmpk_gt_u32 s16, 0x107f
	s_cbranch_scc0 .LBB0_40
	s_cmpk_gt_u32 s16, 0x15ff
	s_cbranch_scc0 .LBB0_37
	s_cmpk_gt_u32 s16, 0x16ff
	s_cbranch_scc0 .LBB0_34
	s_and_b32 s5, s10, 0x1ffc0
	s_and_b32 s4, s8, 0x3e0
	v_add_u32_e32 v36, s5, v20
	s_lshl_b32 s0, s4, 2
	v_ashrrev_i32_e32 v37, 31, v36
	v_lshl_add_u64 v[38:39], v[0:1], 0, s[0:1]
	v_lshlrev_b64 v[36:37], 12, v[36:37]
	v_lshl_add_u64 v[36:37], v[38:39], 0, v[36:37]
	v_add_co_u32_e32 v38, vcc, 0x2000, v36
	s_lshl_b32 s0, s5, 1
	s_nop 0
	v_addc_co_u32_e32 v39, vcc, 0, v37, vcc
	v_add_co_u32_e32 v40, vcc, 0x4000, v36
	s_nop 1
	v_addc_co_u32_e32 v41, vcc, 0, v37, vcc
	v_add_co_u32_e32 v42, vcc, 0x6000, v36
	s_nop 1
	v_addc_co_u32_e32 v43, vcc, 0, v37, vcc
	v_add_co_u32_e32 v44, vcc, 0x8000, v36
	s_nop 1
	v_addc_co_u32_e32 v45, vcc, 0, v37, vcc
	v_add_co_u32_e32 v46, vcc, 0xa000, v36
	s_nop 1
	v_addc_co_u32_e32 v47, vcc, 0, v37, vcc
	v_add_co_u32_e32 v48, vcc, 0xc000, v36
	s_nop 1
	v_addc_co_u32_e32 v49, vcc, 0, v37, vcc
	v_add_co_u32_e32 v50, vcc, 0xe000, v36
	s_nop 1
	v_addc_co_u32_e32 v51, vcc, 0, v37, vcc
	global_load_dword v54, v[36:37], off nt
	global_load_dword v55, v[38:39], off nt
	global_load_dword v56, v[40:41], off nt
	global_load_dword v57, v[42:43], off nt
	global_load_dword v58, v[44:45], off nt
	global_load_dword v59, v[46:47], off nt
	global_load_dword v60, v[48:49], off nt
	global_load_dword v61, v[50:51], off nt
	v_add_co_u32_e32 v38, vcc, 0x10000, v36
	s_nop 1
	v_addc_co_u32_e32 v39, vcc, 0, v37, vcc
	v_add_co_u32_e32 v40, vcc, 0x12000, v36
	s_nop 1
	v_addc_co_u32_e32 v41, vcc, 0, v37, vcc
	v_add_co_u32_e32 v42, vcc, 0x14000, v36
	s_nop 1
	v_addc_co_u32_e32 v43, vcc, 0, v37, vcc
	v_add_co_u32_e32 v44, vcc, 0x16000, v36
	s_nop 1
	v_addc_co_u32_e32 v45, vcc, 0, v37, vcc
	v_add_co_u32_e32 v46, vcc, 0x18000, v36
	s_nop 1
	v_addc_co_u32_e32 v47, vcc, 0, v37, vcc
	v_add_co_u32_e32 v48, vcc, 0x1a000, v36
	s_nop 1
	v_addc_co_u32_e32 v49, vcc, 0, v37, vcc
	v_add_co_u32_e32 v50, vcc, 0x1c000, v36
	s_nop 1
	v_addc_co_u32_e32 v51, vcc, 0, v37, vcc
	v_add_co_u32_e32 v52, vcc, 0x1e000, v36
	s_nop 1
	v_addc_co_u32_e32 v53, vcc, 0, v37, vcc
	global_load_dword v62, v[38:39], off nt
	global_load_dword v63, v[40:41], off nt
	global_load_dword v64, v[42:43], off nt
	global_load_dword v65, v[44:45], off nt
	global_load_dword v66, v[46:47], off nt
	global_load_dword v67, v[48:49], off nt
	global_load_dword v68, v[50:51], off nt
	global_load_dword v69, v[52:53], off nt
	v_add_co_u32_e32 v38, vcc, 0x20000, v36
	s_nop 1
	v_addc_co_u32_e32 v39, vcc, 0, v37, vcc
	v_add_co_u32_e32 v40, vcc, 0x22000, v36
	s_nop 1
	v_addc_co_u32_e32 v41, vcc, 0, v37, vcc
	v_add_co_u32_e32 v42, vcc, 0x24000, v36
	s_nop 1
	v_addc_co_u32_e32 v43, vcc, 0, v37, vcc
	v_add_co_u32_e32 v44, vcc, 0x26000, v36
	s_nop 1
	v_addc_co_u32_e32 v45, vcc, 0, v37, vcc
	v_add_co_u32_e32 v46, vcc, 0x28000, v36
	s_nop 1
	v_addc_co_u32_e32 v47, vcc, 0, v37, vcc
	v_add_co_u32_e32 v48, vcc, 0x2a000, v36
	s_nop 1
	v_addc_co_u32_e32 v49, vcc, 0, v37, vcc
	v_add_co_u32_e32 v50, vcc, 0x2c000, v36
	s_nop 1
	v_addc_co_u32_e32 v51, vcc, 0, v37, vcc
	v_add_co_u32_e32 v52, vcc, 0x2e000, v36
	s_nop 1
	v_addc_co_u32_e32 v53, vcc, 0, v37, vcc
	global_load_dword v70, v[38:39], off nt
	global_load_dword v71, v[40:41], off nt
	global_load_dword v72, v[42:43], off nt
	global_load_dword v73, v[44:45], off nt
	global_load_dword v74, v[46:47], off nt
	global_load_dword v75, v[48:49], off nt
	global_load_dword v76, v[50:51], off nt
	s_nop 0
	global_load_dword v52, v[52:53], off nt
	v_add_co_u32_e32 v38, vcc, 0x30000, v36
	s_nop 1
	v_addc_co_u32_e32 v39, vcc, 0, v37, vcc
	v_add_co_u32_e32 v40, vcc, 0x32000, v36
	s_nop 1
	v_addc_co_u32_e32 v41, vcc, 0, v37, vcc
	v_add_co_u32_e32 v42, vcc, 0x34000, v36
	s_nop 1
	v_addc_co_u32_e32 v43, vcc, 0, v37, vcc
	v_add_co_u32_e32 v44, vcc, 0x36000, v36
	s_nop 1
	v_addc_co_u32_e32 v45, vcc, 0, v37, vcc
	v_add_co_u32_e32 v46, vcc, 0x38000, v36
	s_nop 1
	v_addc_co_u32_e32 v47, vcc, 0, v37, vcc
	v_add_co_u32_e32 v48, vcc, 0x3a000, v36
	s_nop 1
	v_addc_co_u32_e32 v49, vcc, 0, v37, vcc
	v_add_co_u32_e32 v50, vcc, 0x3c000, v36
	s_nop 1
	v_addc_co_u32_e32 v51, vcc, 0, v37, vcc
	v_add_co_u32_e32 v36, vcc, 0x3e000, v36
	s_nop 1
	v_addc_co_u32_e32 v37, vcc, 0, v37, vcc
	global_load_dword v38, v[38:39], off nt
	s_nop 0
	global_load_dword v39, v[40:41], off nt
	s_nop 0
	global_load_dword v40, v[42:43], off nt
	global_load_dword v41, v[44:45], off nt
	s_nop 0
	global_load_dword v42, v[46:47], off nt
	global_load_dword v43, v[48:49], off nt
	global_load_dword v44, v[50:51], off nt
	s_nop 0
	global_load_dword v36, v[36:37], off nt
	s_waitcnt vmcnt(30)
	ds_write2_b32 v21, v54, v55 offset1:66
	s_waitcnt vmcnt(28)
	ds_write2_b32 v21, v56, v57 offset0:132 offset1:198
	s_waitcnt vmcnt(26)
	ds_write2_b32 v27, v58, v59 offset0:8 offset1:74
	s_waitcnt vmcnt(24)
	ds_write2_b32 v27, v60, v61 offset0:140 offset1:206
	s_waitcnt vmcnt(22)
	ds_write2_b32 v28, v62, v63 offset0:16 offset1:82
	s_waitcnt vmcnt(20)
	ds_write2_b32 v28, v64, v65 offset0:148 offset1:214
	s_waitcnt vmcnt(18)
	ds_write2_b32 v29, v66, v67 offset0:24 offset1:90
	s_waitcnt vmcnt(16)
	ds_write2_b32 v29, v68, v69 offset0:156 offset1:222
	s_waitcnt vmcnt(14)
	ds_write2_b32 v30, v70, v71 offset0:32 offset1:98
	s_waitcnt vmcnt(12)
	ds_write2_b32 v30, v72, v73 offset0:164 offset1:230
	s_waitcnt vmcnt(10)
	ds_write2_b32 v31, v74, v75 offset0:40 offset1:106
	s_waitcnt vmcnt(8)
	ds_write2_b32 v31, v76, v52 offset0:172 offset1:238
	s_waitcnt vmcnt(6)
	ds_write2_b32 v32, v38, v39 offset0:48 offset1:114
	s_waitcnt vmcnt(4)
; #define LAS __attribute__((address_space(3)))
; __device__ __forceinline__ unsigned pk2(float lo, float hi) { return f2bf(lo) | (f2bf(hi) << 16); }
; template <bool SCALED> __device__ __forceinline__ void transpose_item_t(const float* W, int K, int N, bf16* WT, int mode, LAS float* scr, int item, int lane, const float* gvec, const float* scv, const float* shv, float* biasp) {
;     ...
; #pragma unroll
;     for (int i = 0; i < 32; ++i) scr[(2 * i + (lane >> 5)) * 33 + (lane & 31)] = tv[i];
;     asm volatile("s_waitcnt lgkmcnt(0)" ::: "memory");
;     const int c = lane & 7;
; #pragma unroll
;     for (int j = 0; j < 4; ++j) { const int n = (lane >> 3) + 8 * j; const LAS float* s = scr + (8 * c) * 33 + n;
;         v4u o; o.x = pk2(s[0 * 33], s[1 * 33]); o.y = pk2(s[2 * 33], s[3 * 33]); o.z = pk2(s[4 * 33], s[5 * 33]); o.w = pk2(s[6 * 33], s[7 * 33]);
;         *(v4u*)(WT + (size_t)(d0 + n) * K + k0 + 8 * c) = o; }
;     asm volatile("s_waitcnt lgkmcnt(0)" ::: "memory");
	ds_write2_b32 v32, v40, v41 offset0:180 offset1:246
	s_waitcnt vmcnt(2)
	ds_write2_b32 v33, v42, v43 offset0:56 offset1:122
	s_waitcnt vmcnt(0)
	ds_write2_b32 v33, v44, v36 offset0:188 offset1:254
	s_waitcnt lgkmcnt(0)
	ds_read2_b32 v[40:41], v23 offset1:8
	ds_read2_b32 v[44:45], v23 offset0:33 offset1:41
	ds_read2_b32 v[46:47], v23 offset0:66 offset1:74
	ds_read2_b32 v[48:49], v23 offset0:99 offset1:107
	ds_read2_b32 v[50:51], v23 offset0:132 offset1:140
	s_waitcnt lgkmcnt(4)
	v_bfe_u32 v36, v40, 16, 1
	v_add3_u32 v36, v40, v36, s12
	s_waitcnt lgkmcnt(3)
	v_bfe_u32 v37, v44, 16, 1
	v_lshrrev_b32_e32 v36, 16, v36
	v_add3_u32 v37, v44, v37, s12
	ds_read2_b32 v[52:53], v23 offset0:165 offset1:173
	v_and_or_b32 v36, v37, s13, v36
	s_waitcnt lgkmcnt(3)
	v_bfe_u32 v37, v46, 16, 1
	v_add3_u32 v37, v46, v37, s12
	s_waitcnt lgkmcnt(2)
	v_bfe_u32 v38, v48, 16, 1
	ds_read2_b32 v[54:55], v23 offset0:198 offset1:206
	v_lshrrev_b32_e32 v37, 16, v37
	v_add3_u32 v38, v48, v38, s12
	ds_read2_b32 v[56:57], v23 offset0:231 offset1:239
	v_and_or_b32 v37, v38, s13, v37
	s_waitcnt lgkmcnt(3)
	v_bfe_u32 v38, v50, 16, 1
	v_add3_u32 v38, v50, v38, s12
	s_waitcnt lgkmcnt(2)
	v_bfe_u32 v39, v52, 16, 1
	v_lshrrev_b32_e32 v38, 16, v38
	v_add3_u32 v39, v52, v39, s12
	v_and_or_b32 v38, v39, s13, v38
	s_waitcnt lgkmcnt(1)
	v_bfe_u32 v39, v54, 16, 1
	v_add_u32_e32 v58, s4, v22
	v_add3_u32 v39, v54, v39, s12
	s_waitcnt lgkmcnt(0)
	v_bfe_u32 v40, v56, 16, 1
	v_ashrrev_i32_e32 v59, 31, v58
	v_lshl_add_u64 v[42:43], v[2:3], 0, s[0:1]
	v_lshrrev_b32_e32 v39, 16, v39
	v_add3_u32 v40, v56, v40, s12
	v_lshlrev_b64 v[58:59], 11, v[58:59]
	v_and_or_b32 v39, v40, s13, v39
	v_lshl_add_u64 v[58:59], v[42:43], 0, v[58:59]
	global_store_dwordx4 v[58:59], v[36:39], off
	v_bfe_u32 v40, v57, 16, 1
	v_add3_u32 v40, v57, v40, s12
	v_bfe_u32 v36, v41, 16, 1
	v_add3_u32 v36, v41, v36, s12
	v_bfe_u32 v37, v45, 16, 1
	v_lshrrev_b32_e32 v36, 16, v36
	v_add3_u32 v37, v45, v37, s12
	v_and_or_b32 v36, v37, s13, v36
	v_bfe_u32 v37, v47, 16, 1
	v_add3_u32 v37, v47, v37, s12
	v_bfe_u32 v38, v49, 16, 1
	v_lshrrev_b32_e32 v37, 16, v37
	v_add3_u32 v38, v49, v38, s12
	v_and_or_b32 v37, v38, s13, v37
	v_bfe_u32 v38, v51, 16, 1
	v_add3_u32 v38, v51, v38, s12
	v_bfe_u32 v39, v53, 16, 1
	v_lshrrev_b32_e32 v38, 16, v38
	v_add3_u32 v39, v53, v39, s12
	v_and_or_b32 v38, v39, s13, v38
	v_bfe_u32 v39, v55, 16, 1
	v_add3_u32 v39, v55, v39, s12
	v_lshrrev_b32_e32 v39, 16, v39
	v_and_or_b32 v39, v40, s13, v39
	v_add_u32_e32 v40, s4, v24
	v_ashrrev_i32_e32 v41, 31, v40
	v_lshlrev_b64 v[40:41], 11, v[40:41]
	ds_read2_b32 v[44:45], v23 offset0:16 offset1:24
	v_lshl_add_u64 v[40:41], v[42:43], 0, v[40:41]
	global_store_dwordx4 v[40:41], v[36:39], off
	ds_read2_b32 v[40:41], v23 offset0:49 offset1:57
	ds_read2_b32 v[46:47], v23 offset0:82 offset1:90
	ds_read2_b32 v[48:49], v23 offset0:115 offset1:123
	s_waitcnt lgkmcnt(3)
	v_bfe_u32 v36, v44, 16, 1
	v_add3_u32 v36, v44, v36, s12
	s_waitcnt lgkmcnt(2)
	v_bfe_u32 v37, v40, 16, 1
	ds_read2_b32 v[50:51], v23 offset0:148 offset1:156
	v_lshrrev_b32_e32 v36, 16, v36
	v_add3_u32 v37, v40, v37, s12
	ds_read2_b32 v[52:53], v23 offset0:181 offset1:189
	v_and_or_b32 v36, v37, s13, v36
	s_waitcnt lgkmcnt(3)
	v_bfe_u32 v37, v46, 16, 1
	v_add3_u32 v37, v46, v37, s12
	s_waitcnt lgkmcnt(2)
	v_bfe_u32 v38, v48, 16, 1
	ds_read2_b32 v[54:55], v23 offset0:214 offset1:222
	v_lshrrev_b32_e32 v37, 16, v37
	v_add3_u32 v38, v48, v38, s12
	ds_read2_b32 v[56:57], v23 offset0:247 offset1:255
	v_and_or_b32 v37, v38, s13, v37
	s_waitcnt lgkmcnt(3)
	v_bfe_u32 v38, v50, 16, 1
	v_add3_u32 v38, v50, v38, s12
	s_waitcnt lgkmcnt(2)
	v_bfe_u32 v39, v52, 16, 1
	v_lshrrev_b32_e32 v38, 16, v38
	v_add3_u32 v39, v52, v39, s12
	v_and_or_b32 v38, v39, s13, v38
	s_waitcnt lgkmcnt(1)
	v_bfe_u32 v39, v54, 16, 1
	v_add_u32_e32 v58, s4, v25
	v_add3_u32 v39, v54, v39, s12
	s_waitcnt lgkmcnt(0)
	v_bfe_u32 v40, v56, 16, 1
	v_ashrrev_i32_e32 v59, 31, v58
	v_lshrrev_b32_e32 v39, 16, v39
	v_add3_u32 v40, v56, v40, s12
	v_lshlrev_b64 v[58:59], 11, v[58:59]
	v_and_or_b32 v39, v40, s13, v39
	v_lshl_add_u64 v[58:59], v[42:43], 0, v[58:59]
	global_store_dwordx4 v[58:59], v[36:39], off
	v_bfe_u32 v40, v57, 16, 1
	v_add3_u32 v40, v57, v40, s12
	v_bfe_u32 v36, v45, 16, 1
	v_add3_u32 v36, v45, v36, s12
	v_bfe_u32 v37, v41, 16, 1
	v_lshrrev_b32_e32 v36, 16, v36
	v_add3_u32 v37, v41, v37, s12
	v_and_or_b32 v36, v37, s13, v36
	v_bfe_u32 v37, v47, 16, 1
	v_add3_u32 v37, v47, v37, s12
	v_bfe_u32 v38, v49, 16, 1
	v_lshrrev_b32_e32 v37, 16, v37
	v_add3_u32 v38, v49, v38, s12
	v_and_or_b32 v37, v38, s13, v37
	v_bfe_u32 v38, v51, 16, 1
	v_add3_u32 v38, v51, v38, s12
	v_bfe_u32 v39, v53, 16, 1
	v_lshrrev_b32_e32 v38, 16, v38
	v_add3_u32 v39, v53, v39, s12
	v_and_or_b32 v38, v39, s13, v38
	v_bfe_u32 v39, v55, 16, 1
	v_add3_u32 v39, v55, v39, s12
	v_lshrrev_b32_e32 v39, 16, v39
	v_and_or_b32 v39, v40, s13, v39
	v_add_u32_e32 v40, s4, v26
	v_ashrrev_i32_e32 v41, 31, v40
	v_lshlrev_b64 v[40:41], 11, v[40:41]
	v_lshl_add_u64 v[40:41], v[42:43], 0, v[40:41]
	global_store_dwordx4 v[40:41], v[36:39], off
	s_waitcnt lgkmcnt(0)
	s_mov_b64 s[4:5], 0
; #define LAS __attribute__((address_space(3)))
; __device__ __forceinline__ void transpose_item(const float* W, int K, int N, bf16* WT, int mode, LAS float* scr, int item, int lane) { transpose_item_t<false>(W, K, N, WT, mode, scr, item, lane, nullptr, nullptr, nullptr, nullptr); }
; template <bool SCALED> __device__ __forceinline__ void transpose_item_t(const float* W, int K, int N, bf16* WT, int mode, LAS float* scr, int item, int lane, const float* gvec, const float* scv, const float* shv, float* biasp) {
;     const int nblk = N / 32, kb = item / nblk, nb = item % nblk, k0 = 64 * kb, n0 = 32 * nb, d0 = dst_row0(mode, n0);
;     float tv[32];
; #pragma unroll
;     for (int i = 0; i < 32; ++i) tv[i] = W[(size_t)(k0 + 2 * i + (lane >> 5)) * N + n0 + (lane & 31)];
; __global__ void __launch_bounds__(512, 2) hybrid_fwd(Args args) {
;     ...
;             if (r < I_A0) { transpose_item(w_attn_out, AW, DM, WA, 0, scr, r, lane); continue; } r -= I_A0;
.LBB0_34:
	s_andn2_b64 vcc, exec, s[4:5]
	s_cbranch_vccnz .LBB0_36
	s_add_i32 s0, s10, 0xfffe2e00
	s_and_b32 s5, s0, 0x1c0
	s_and_b32 s4, s8, 0x3e0
	v_add_u32_e32 v36, s5, v20
	s_lshl_b32 s0, s4, 2
	v_ashrrev_i32_e32 v37, 31, v36
	v_lshl_add_u64 v[38:39], v[4:5], 0, s[0:1]
	v_lshlrev_b64 v[36:37], 12, v[36:37]
	v_lshl_add_u64 v[36:37], v[38:39], 0, v[36:37]
	v_add_co_u32_e32 v38, vcc, 0x2000, v36
	s_lshl_b32 s0, s5, 1
	s_nop 0
	v_addc_co_u32_e32 v39, vcc, 0, v37, vcc
	v_add_co_u32_e32 v40, vcc, 0x4000, v36
	s_nop 1
	v_addc_co_u32_e32 v41, vcc, 0, v37, vcc
	v_add_co_u32_e32 v42, vcc, 0x6000, v36
	s_nop 1
	v_addc_co_u32_e32 v43, vcc, 0, v37, vcc
	v_add_co_u32_e32 v44, vcc, 0x8000, v36
	s_nop 1
	v_addc_co_u32_e32 v45, vcc, 0, v37, vcc
	v_add_co_u32_e32 v46, vcc, 0xa000, v36
	s_nop 1
	v_addc_co_u32_e32 v47, vcc, 0, v37, vcc
	v_add_co_u32_e32 v48, vcc, 0xc000, v36
	s_nop 1
	v_addc_co_u32_e32 v49, vcc, 0, v37, vcc
	v_add_co_u32_e32 v50, vcc, 0xe000, v36
	s_nop 1
	v_addc_co_u32_e32 v51, vcc, 0, v37, vcc
	global_load_dword v54, v[36:37], off nt
	global_load_dword v55, v[38:39], off nt
	global_load_dword v56, v[40:41], off nt
	global_load_dword v57, v[42:43], off nt
	global_load_dword v58, v[44:45], off nt
	global_load_dword v59, v[46:47], off nt
	global_load_dword v60, v[48:49], off nt
	global_load_dword v61, v[50:51], off nt
	v_add_co_u32_e32 v38, vcc, 0x10000, v36
	s_nop 1
	v_addc_co_u32_e32 v39, vcc, 0, v37, vcc
	v_add_co_u32_e32 v40, vcc, 0x12000, v36
	s_nop 1
	v_addc_co_u32_e32 v41, vcc, 0, v37, vcc
	v_add_co_u32_e32 v42, vcc, 0x14000, v36
	s_nop 1
	v_addc_co_u32_e32 v43, vcc, 0, v37, vcc
	v_add_co_u32_e32 v44, vcc, 0x16000, v36
	s_nop 1
	v_addc_co_u32_e32 v45, vcc, 0, v37, vcc
	v_add_co_u32_e32 v46, vcc, 0x18000, v36
	s_nop 1
	v_addc_co_u32_e32 v47, vcc, 0, v37, vcc
	v_add_co_u32_e32 v48, vcc, 0x1a000, v36
	s_nop 1
	v_addc_co_u32_e32 v49, vcc, 0, v37, vcc
	v_add_co_u32_e32 v50, vcc, 0x1c000, v36
	s_nop 1
	v_addc_co_u32_e32 v51, vcc, 0, v37, vcc
	v_add_co_u32_e32 v52, vcc, 0x1e000, v36
	s_nop 1
	v_addc_co_u32_e32 v53, vcc, 0, v37, vcc
	global_load_dword v62, v[38:39], off nt
	global_load_dword v63, v[40:41], off nt
	global_load_dword v64, v[42:43], off nt
	global_load_dword v65, v[44:45], off nt
	global_load_dword v66, v[46:47], off nt
	global_load_dword v67, v[48:49], off nt
	global_load_dword v68, v[50:51], off nt
	global_load_dword v69, v[52:53], off nt
	v_add_co_u32_e32 v38, vcc, 0x20000, v36
	s_nop 1
	v_addc_co_u32_e32 v39, vcc, 0, v37, vcc
	v_add_co_u32_e32 v40, vcc, 0x22000, v36
	s_nop 1
	v_addc_co_u32_e32 v41, vcc, 0, v37, vcc
	v_add_co_u32_e32 v42, vcc, 0x24000, v36
	s_nop 1
	v_addc_co_u32_e32 v43, vcc, 0, v37, vcc
	v_add_co_u32_e32 v44, vcc, 0x26000, v36
	s_nop 1
	v_addc_co_u32_e32 v45, vcc, 0, v37, vcc
	v_add_co_u32_e32 v46, vcc, 0x28000, v36
	s_nop 1
	v_addc_co_u32_e32 v47, vcc, 0, v37, vcc
	v_add_co_u32_e32 v48, vcc, 0x2a000, v36
	s_nop 1
	v_addc_co_u32_e32 v49, vcc, 0, v37, vcc
	v_add_co_u32_e32 v50, vcc, 0x2c000, v36
	s_nop 1
	v_addc_co_u32_e32 v51, vcc, 0, v37, vcc
	v_add_co_u32_e32 v52, vcc, 0x2e000, v36
	s_nop 1
	v_addc_co_u32_e32 v53, vcc, 0, v37, vcc
	global_load_dword v70, v[38:39], off nt
	global_load_dword v71, v[40:41], off nt
	global_load_dword v72, v[42:43], off nt
	global_load_dword v73, v[44:45], off nt
	global_load_dword v74, v[46:47], off nt
	global_load_dword v75, v[48:49], off nt
	global_load_dword v76, v[50:51], off nt
	s_nop 0
	global_load_dword v52, v[52:53], off nt
	v_add_co_u32_e32 v38, vcc, 0x30000, v36
	s_nop 1
	v_addc_co_u32_e32 v39, vcc, 0, v37, vcc
	v_add_co_u32_e32 v40, vcc, 0x32000, v36
	s_nop 1
	v_addc_co_u32_e32 v41, vcc, 0, v37, vcc
	v_add_co_u32_e32 v42, vcc, 0x34000, v36
	s_nop 1
	v_addc_co_u32_e32 v43, vcc, 0, v37, vcc
	v_add_co_u32_e32 v44, vcc, 0x36000, v36
	s_nop 1
	v_addc_co_u32_e32 v45, vcc, 0, v37, vcc
	v_add_co_u32_e32 v46, vcc, 0x38000, v36
	s_nop 1
	v_addc_co_u32_e32 v47, vcc, 0, v37, vcc
	v_add_co_u32_e32 v48, vcc, 0x3a000, v36
	s_nop 1
	v_addc_co_u32_e32 v49, vcc, 0, v37, vcc
	v_add_co_u32_e32 v50, vcc, 0x3c000, v36
	s_nop 1
	v_addc_co_u32_e32 v51, vcc, 0, v37, vcc
	v_add_co_u32_e32 v36, vcc, 0x3e000, v36
	s_nop 1
	v_addc_co_u32_e32 v37, vcc, 0, v37, vcc
	global_load_dword v38, v[38:39], off nt
	s_nop 0
	global_load_dword v39, v[40:41], off nt
	s_nop 0
	global_load_dword v40, v[42:43], off nt
	global_load_dword v41, v[44:45], off nt
	s_nop 0
	global_load_dword v42, v[46:47], off nt
	global_load_dword v43, v[48:49], off nt
	global_load_dword v44, v[50:51], off nt
	s_nop 0
	global_load_dword v36, v[36:37], off nt
	s_waitcnt vmcnt(30)
	ds_write2_b32 v21, v54, v55 offset1:66
	s_waitcnt vmcnt(28)
	ds_write2_b32 v21, v56, v57 offset0:132 offset1:198
	s_waitcnt vmcnt(26)
	ds_write2_b32 v27, v58, v59 offset0:8 offset1:74
	s_waitcnt vmcnt(24)
	ds_write2_b32 v27, v60, v61 offset0:140 offset1:206
	s_waitcnt vmcnt(22)
	ds_write2_b32 v28, v62, v63 offset0:16 offset1:82
	s_waitcnt vmcnt(20)
	ds_write2_b32 v28, v64, v65 offset0:148 offset1:214
	s_waitcnt vmcnt(18)
	ds_write2_b32 v29, v66, v67 offset0:24 offset1:90
	s_waitcnt vmcnt(16)
	ds_write2_b32 v29, v68, v69 offset0:156 offset1:222
	s_waitcnt vmcnt(14)
	ds_write2_b32 v30, v70, v71 offset0:32 offset1:98
	s_waitcnt vmcnt(12)
	ds_write2_b32 v30, v72, v73 offset0:164 offset1:230
	s_waitcnt vmcnt(10)
; #define LAS __attribute__((address_space(3)))
; __device__ __forceinline__ unsigned pk2(float lo, float hi) { return f2bf(lo) | (f2bf(hi) << 16); }
; template <bool SCALED> __device__ __forceinline__ void transpose_item_t(const float* W, int K, int N, bf16* WT, int mode, LAS float* scr, int item, int lane, const float* gvec, const float* scv, const float* shv, float* biasp) {
;     ...
; #pragma unroll
;     for (int i = 0; i < 32; ++i) scr[(2 * i + (lane >> 5)) * 33 + (lane & 31)] = tv[i];
;     asm volatile("s_waitcnt lgkmcnt(0)" ::: "memory");
;     const int c = lane & 7;
; #pragma unroll
;     for (int j = 0; j < 4; ++j) { const int n = (lane >> 3) + 8 * j; const LAS float* s = scr + (8 * c) * 33 + n;
;         v4u o; o.x = pk2(s[0 * 33], s[1 * 33]); o.y = pk2(s[2 * 33], s[3 * 33]); o.z = pk2(s[4 * 33], s[5 * 33]); o.w = pk2(s[6 * 33], s[7 * 33]);
;         *(v4u*)(WT + (size_t)(d0 + n) * K + k0 + 8 * c) = o; }
;     asm volatile("s_waitcnt lgkmcnt(0)" ::: "memory");
	ds_write2_b32 v31, v74, v75 offset0:40 offset1:106
	s_waitcnt vmcnt(8)
	ds_write2_b32 v31, v76, v52 offset0:172 offset1:238
	s_waitcnt vmcnt(6)
	ds_write2_b32 v32, v38, v39 offset0:48 offset1:114
	s_waitcnt vmcnt(4)
	ds_write2_b32 v32, v40, v41 offset0:180 offset1:246
	s_waitcnt vmcnt(2)
	ds_write2_b32 v33, v42, v43 offset0:56 offset1:122
	s_waitcnt vmcnt(0)
	ds_write2_b32 v33, v44, v36 offset0:188 offset1:254
	s_waitcnt lgkmcnt(0)
	ds_read2_b32 v[40:41], v23 offset1:8
	ds_read2_b32 v[44:45], v23 offset0:33 offset1:41
	ds_read2_b32 v[46:47], v23 offset0:66 offset1:74
	ds_read2_b32 v[48:49], v23 offset0:99 offset1:107
	ds_read2_b32 v[50:51], v23 offset0:132 offset1:140
	s_waitcnt lgkmcnt(4)
	v_bfe_u32 v36, v40, 16, 1
	v_add3_u32 v36, v40, v36, s12
	s_waitcnt lgkmcnt(3)
	v_bfe_u32 v37, v44, 16, 1
	v_lshrrev_b32_e32 v36, 16, v36
	v_add3_u32 v37, v44, v37, s12
	ds_read2_b32 v[52:53], v23 offset0:165 offset1:173
	v_and_or_b32 v36, v37, s13, v36
	s_waitcnt lgkmcnt(3)
	v_bfe_u32 v37, v46, 16, 1
	v_add3_u32 v37, v46, v37, s12
	s_waitcnt lgkmcnt(2)
	v_bfe_u32 v38, v48, 16, 1
	ds_read2_b32 v[54:55], v23 offset0:198 offset1:206
	v_lshrrev_b32_e32 v37, 16, v37
	v_add3_u32 v38, v48, v38, s12
	ds_read2_b32 v[56:57], v23 offset0:231 offset1:239
	v_and_or_b32 v37, v38, s13, v37
	s_waitcnt lgkmcnt(3)
	v_bfe_u32 v38, v50, 16, 1
	v_add3_u32 v38, v50, v38, s12
	s_waitcnt lgkmcnt(2)
	v_bfe_u32 v39, v52, 16, 1
	v_lshrrev_b32_e32 v38, 16, v38
	v_add3_u32 v39, v52, v39, s12
	v_and_or_b32 v38, v39, s13, v38
	s_waitcnt lgkmcnt(1)
	v_bfe_u32 v39, v54, 16, 1
	v_add_u32_e32 v58, s4, v22
	v_add3_u32 v39, v54, v39, s12
	s_waitcnt lgkmcnt(0)
	v_bfe_u32 v40, v56, 16, 1
	v_ashrrev_i32_e32 v59, 31, v58
	v_lshl_add_u64 v[42:43], v[6:7], 0, s[0:1]
	v_lshrrev_b32_e32 v39, 16, v39
	v_add3_u32 v40, v56, v40, s12
	v_lshlrev_b64 v[58:59], 10, v[58:59]
	v_and_or_b32 v39, v40, s13, v39
	v_lshl_add_u64 v[58:59], v[42:43], 0, v[58:59]
	global_store_dwordx4 v[58:59], v[36:39], off
	v_bfe_u32 v40, v57, 16, 1
	v_add3_u32 v40, v57, v40, s12
	v_bfe_u32 v36, v41, 16, 1
	v_add3_u32 v36, v41, v36, s12
	v_bfe_u32 v37, v45, 16, 1
	v_lshrrev_b32_e32 v36, 16, v36
	v_add3_u32 v37, v45, v37, s12
	v_and_or_b32 v36, v37, s13, v36
	v_bfe_u32 v37, v47, 16, 1
	v_add3_u32 v37, v47, v37, s12
	v_bfe_u32 v38, v49, 16, 1
	v_lshrrev_b32_e32 v37, 16, v37
	v_add3_u32 v38, v49, v38, s12
	v_and_or_b32 v37, v38, s13, v37
	v_bfe_u32 v38, v51, 16, 1
	v_add3_u32 v38, v51, v38, s12
	v_bfe_u32 v39, v53, 16, 1
	v_lshrrev_b32_e32 v38, 16, v38
	v_add3_u32 v39, v53, v39, s12
	v_and_or_b32 v38, v39, s13, v38
	v_bfe_u32 v39, v55, 16, 1
	v_add3_u32 v39, v55, v39, s12
	v_lshrrev_b32_e32 v39, 16, v39
	v_and_or_b32 v39, v40, s13, v39
	v_add_u32_e32 v40, s4, v24
	v_ashrrev_i32_e32 v41, 31, v40
	v_lshlrev_b64 v[40:41], 10, v[40:41]
	ds_read2_b32 v[44:45], v23 offset0:16 offset1:24
	v_lshl_add_u64 v[40:41], v[42:43], 0, v[40:41]
	global_store_dwordx4 v[40:41], v[36:39], off
	ds_read2_b32 v[40:41], v23 offset0:49 offset1:57
	ds_read2_b32 v[46:47], v23 offset0:82 offset1:90
	ds_read2_b32 v[48:49], v23 offset0:115 offset1:123
	s_waitcnt lgkmcnt(3)
	v_bfe_u32 v36, v44, 16, 1
	v_add3_u32 v36, v44, v36, s12
	s_waitcnt lgkmcnt(2)
	v_bfe_u32 v37, v40, 16, 1
	ds_read2_b32 v[50:51], v23 offset0:148 offset1:156
	v_lshrrev_b32_e32 v36, 16, v36
	v_add3_u32 v37, v40, v37, s12
	ds_read2_b32 v[52:53], v23 offset0:181 offset1:189
	v_and_or_b32 v36, v37, s13, v36
	s_waitcnt lgkmcnt(3)
	v_bfe_u32 v37, v46, 16, 1
	v_add3_u32 v37, v46, v37, s12
	s_waitcnt lgkmcnt(2)
	v_bfe_u32 v38, v48, 16, 1
	ds_read2_b32 v[54:55], v23 offset0:214 offset1:222
	v_lshrrev_b32_e32 v37, 16, v37
	v_add3_u32 v38, v48, v38, s12
	ds_read2_b32 v[56:57], v23 offset0:247 offset1:255
	v_and_or_b32 v37, v38, s13, v37
	s_waitcnt lgkmcnt(3)
	v_bfe_u32 v38, v50, 16, 1
	v_add3_u32 v38, v50, v38, s12
	s_waitcnt lgkmcnt(2)
	v_bfe_u32 v39, v52, 16, 1
	v_lshrrev_b32_e32 v38, 16, v38
	v_add3_u32 v39, v52, v39, s12
	v_and_or_b32 v38, v39, s13, v38
	s_waitcnt lgkmcnt(1)
	v_bfe_u32 v39, v54, 16, 1
	v_add_u32_e32 v58, s4, v25
	v_add3_u32 v39, v54, v39, s12
	s_waitcnt lgkmcnt(0)
	v_bfe_u32 v40, v56, 16, 1
	v_ashrrev_i32_e32 v59, 31, v58
	v_lshrrev_b32_e32 v39, 16, v39
	v_add3_u32 v40, v56, v40, s12
	v_lshlrev_b64 v[58:59], 10, v[58:59]
	v_and_or_b32 v39, v40, s13, v39
	v_lshl_add_u64 v[58:59], v[42:43], 0, v[58:59]
	global_store_dwordx4 v[58:59], v[36:39], off
	v_bfe_u32 v40, v57, 16, 1
	v_add3_u32 v40, v57, v40, s12
	v_bfe_u32 v36, v45, 16, 1
	v_add3_u32 v36, v45, v36, s12
	v_bfe_u32 v37, v41, 16, 1
	v_lshrrev_b32_e32 v36, 16, v36
	v_add3_u32 v37, v41, v37, s12
	v_and_or_b32 v36, v37, s13, v36
	v_bfe_u32 v37, v47, 16, 1
	v_add3_u32 v37, v47, v37, s12
	v_bfe_u32 v38, v49, 16, 1
	v_lshrrev_b32_e32 v37, 16, v37
	v_add3_u32 v38, v49, v38, s12
	v_and_or_b32 v37, v38, s13, v37
	v_bfe_u32 v38, v51, 16, 1
	v_add3_u32 v38, v51, v38, s12
	v_bfe_u32 v39, v53, 16, 1
	v_lshrrev_b32_e32 v38, 16, v38
	v_add3_u32 v39, v53, v39, s12
	v_and_or_b32 v38, v39, s13, v38
	v_bfe_u32 v39, v55, 16, 1
	v_add3_u32 v39, v55, v39, s12
	v_lshrrev_b32_e32 v39, 16, v39
	v_and_or_b32 v39, v40, s13, v39
	v_add_u32_e32 v40, s4, v26
	v_ashrrev_i32_e32 v41, 31, v40
	v_lshlrev_b64 v[40:41], 10, v[40:41]
	v_lshl_add_u64 v[40:41], v[42:43], 0, v[40:41]
	global_store_dwordx4 v[40:41], v[36:39], off
	s_waitcnt lgkmcnt(0)

; #define LAS __attribute__((address_space(3)))
; __device__ __forceinline__ void transpose_item(const float* W, int K, int N, bf16* WT, int mode, LAS float* scr, int item, int lane) { transpose_item_t<false>(W, K, N, WT, mode, scr, item, lane, nullptr, nullptr, nullptr, nullptr); }
; template <bool SCALED> __device__ __forceinline__ void transpose_item_t(const float* W, int K, int N, bf16* WT, int mode, LAS float* scr, int item, int lane, const float* gvec, const float* scv, const float* shv, float* biasp) {
;     const int nblk = N / 32, kb = item / nblk, nb = item % nblk, k0 = 64 * kb, n0 = 32 * nb, d0 = dst_row0(mode, n0);
;     float tv[32];
; #pragma unroll
;     for (int i = 0; i < 32; ++i) tv[i] = W[(size_t)(k0 + 2 * i + (lane >> 5)) * N + n0 + (lane & 31)];
; __global__ void __launch_bounds__(512, 2) hybrid_fwd(Args args) {
;     ...
;             if (r < I_4) { transpose_item(w_ffn2_out, DFF, DM, W4, 0, scr, r, lane); continue; } r -= I_4;
.LBB0_37:
	s_andn2_b64 vcc, exec, s[4:5]
	s_cbranch_vccnz .LBB0_39
	s_add_i32 s0, s10, 0xd00
	s_and_b32 s5, s0, 0x1ffc0
	s_and_b32 s4, s8, 0x3e0
	v_add_u32_e32 v36, s5, v20
	s_lshl_b32 s0, s4, 2
	v_ashrrev_i32_e32 v37, 31, v36
	v_lshl_add_u64 v[38:39], v[8:9], 0, s[0:1]
	v_lshlrev_b64 v[36:37], 12, v[36:37]
	v_lshl_add_u64 v[36:37], v[38:39], 0, v[36:37]
	v_add_co_u32_e32 v38, vcc, 0x2000, v36
	s_lshl_b32 s0, s5, 1
	s_nop 0
	v_addc_co_u32_e32 v39, vcc, 0, v37, vcc
	v_add_co_u32_e32 v40, vcc, 0x4000, v36
	s_nop 1
	v_addc_co_u32_e32 v41, vcc, 0, v37, vcc
	v_add_co_u32_e32 v42, vcc, 0x6000, v36
	s_nop 1
	v_addc_co_u32_e32 v43, vcc, 0, v37, vcc
	v_add_co_u32_e32 v44, vcc, 0x8000, v36
	s_nop 1
	v_addc_co_u32_e32 v45, vcc, 0, v37, vcc
	v_add_co_u32_e32 v46, vcc, 0xa000, v36
	s_nop 1
	v_addc_co_u32_e32 v47, vcc, 0, v37, vcc
	v_add_co_u32_e32 v48, vcc, 0xc000, v36
	s_nop 1
	v_addc_co_u32_e32 v49, vcc, 0, v37, vcc
	v_add_co_u32_e32 v50, vcc, 0xe000, v36
	s_nop 1
	v_addc_co_u32_e32 v51, vcc, 0, v37, vcc
	global_load_dword v54, v[36:37], off nt
	global_load_dword v55, v[38:39], off nt
	global_load_dword v56, v[40:41], off nt
	global_load_dword v57, v[42:43], off nt
	global_load_dword v58, v[44:45], off nt
	global_load_dword v59, v[46:47], off nt
	global_load_dword v60, v[48:49], off nt
	global_load_dword v61, v[50:51], off nt
	v_add_co_u32_e32 v38, vcc, 0x10000, v36
	s_nop 1
	v_addc_co_u32_e32 v39, vcc, 0, v37, vcc
	v_add_co_u32_e32 v40, vcc, 0x12000, v36
	s_nop 1
	v_addc_co_u32_e32 v41, vcc, 0, v37, vcc
	v_add_co_u32_e32 v42, vcc, 0x14000, v36
	s_nop 1
	v_addc_co_u32_e32 v43, vcc, 0, v37, vcc
	v_add_co_u32_e32 v44, vcc, 0x16000, v36
	s_nop 1
	v_addc_co_u32_e32 v45, vcc, 0, v37, vcc
	v_add_co_u32_e32 v46, vcc, 0x18000, v36
	s_nop 1
	v_addc_co_u32_e32 v47, vcc, 0, v37, vcc
	v_add_co_u32_e32 v48, vcc, 0x1a000, v36
	s_nop 1
	v_addc_co_u32_e32 v49, vcc, 0, v37, vcc
	v_add_co_u32_e32 v50, vcc, 0x1c000, v36
	s_nop 1
	v_addc_co_u32_e32 v51, vcc, 0, v37, vcc
	v_add_co_u32_e32 v52, vcc, 0x1e000, v36
	s_nop 1
	v_addc_co_u32_e32 v53, vcc, 0, v37, vcc
	global_load_dword v62, v[38:39], off nt
	global_load_dword v63, v[40:41], off nt
	global_load_dword v64, v[42:43], off nt
	global_load_dword v65, v[44:45], off nt
	global_load_dword v66, v[46:47], off nt
	global_load_dword v67, v[48:49], off nt
	global_load_dword v68, v[50:51], off nt
	global_load_dword v69, v[52:53], off nt
	v_add_co_u32_e32 v38, vcc, 0x20000, v36
	s_nop 1
	v_addc_co_u32_e32 v39, vcc, 0, v37, vcc
	v_add_co_u32_e32 v40, vcc, 0x22000, v36
	s_nop 1
	v_addc_co_u32_e32 v41, vcc, 0, v37, vcc
	v_add_co_u32_e32 v42, vcc, 0x24000, v36
	s_nop 1
	v_addc_co_u32_e32 v43, vcc, 0, v37, vcc
	v_add_co_u32_e32 v44, vcc, 0x26000, v36
	s_nop 1
	v_addc_co_u32_e32 v45, vcc, 0, v37, vcc
	v_add_co_u32_e32 v46, vcc, 0x28000, v36
	s_nop 1
	v_addc_co_u32_e32 v47, vcc, 0, v37, vcc
	v_add_co_u32_e32 v48, vcc, 0x2a000, v36
	s_nop 1
	v_addc_co_u32_e32 v49, vcc, 0, v37, vcc
	v_add_co_u32_e32 v50, vcc, 0x2c000, v36
	s_nop 1
	v_addc_co_u32_e32 v51, vcc, 0, v37, vcc
	v_add_co_u32_e32 v52, vcc, 0x2e000, v36
	s_nop 1
	v_addc_co_u32_e32 v53, vcc, 0, v37, vcc
	global_load_dword v70, v[38:39], off nt
	global_load_dword v71, v[40:41], off nt
	global_load_dword v72, v[42:43], off nt
	global_load_dword v73, v[44:45], off nt
	global_load_dword v74, v[46:47], off nt
	global_load_dword v75, v[48:49], off nt
	global_load_dword v76, v[50:51], off nt
	s_nop 0
	global_load_dword v52, v[52:53], off nt
	v_add_co_u32_e32 v38, vcc, 0x30000, v36
	s_nop 1
	v_addc_co_u32_e32 v39, vcc, 0, v37, vcc
	v_add_co_u32_e32 v40, vcc, 0x32000, v36
	s_nop 1
	v_addc_co_u32_e32 v41, vcc, 0, v37, vcc
	v_add_co_u32_e32 v42, vcc, 0x34000, v36
	s_nop 1
	v_addc_co_u32_e32 v43, vcc, 0, v37, vcc
	v_add_co_u32_e32 v44, vcc, 0x36000, v36
	s_nop 1
	v_addc_co_u32_e32 v45, vcc, 0, v37, vcc
	v_add_co_u32_e32 v46, vcc, 0x38000, v36
	s_nop 1
	v_addc_co_u32_e32 v47, vcc, 0, v37, vcc
	v_add_co_u32_e32 v48, vcc, 0x3a000, v36
	s_nop 1
	v_addc_co_u32_e32 v49, vcc, 0, v37, vcc
	v_add_co_u32_e32 v50, vcc, 0x3c000, v36
	s_nop 1
	v_addc_co_u32_e32 v51, vcc, 0, v37, vcc
	v_add_co_u32_e32 v36, vcc, 0x3e000, v36
	s_nop 1
	v_addc_co_u32_e32 v37, vcc, 0, v37, vcc
	global_load_dword v38, v[38:39], off nt
	s_nop 0
	global_load_dword v39, v[40:41], off nt
	s_nop 0
	global_load_dword v40, v[42:43], off nt
	global_load_dword v41, v[44:45], off nt
	s_nop 0
	global_load_dword v42, v[46:47], off nt
	global_load_dword v43, v[48:49], off nt
	global_load_dword v44, v[50:51], off nt
	s_nop 0
	global_load_dword v36, v[36:37], off nt
	s_waitcnt vmcnt(30)
	ds_write2_b32 v21, v54, v55 offset1:66
	s_waitcnt vmcnt(28)
	ds_write2_b32 v21, v56, v57 offset0:132 offset1:198
	s_waitcnt vmcnt(26)
	ds_write2_b32 v27, v58, v59 offset0:8 offset1:74
	s_waitcnt vmcnt(24)
	ds_write2_b32 v27, v60, v61 offset0:140 offset1:206
	s_waitcnt vmcnt(22)
	ds_write2_b32 v28, v62, v63 offset0:16 offset1:82
	s_waitcnt vmcnt(20)
	ds_write2_b32 v28, v64, v65 offset0:148 offset1:214
	s_waitcnt vmcnt(18)
	ds_write2_b32 v29, v66, v67 offset0:24 offset1:90
	s_waitcnt vmcnt(16)
	ds_write2_b32 v29, v68, v69 offset0:156 offset1:222
	s_waitcnt vmcnt(14)
; #define LAS __attribute__((address_space(3)))
; __device__ __forceinline__ unsigned pk2(float lo, float hi) { return f2bf(lo) | (f2bf(hi) << 16); }
; template <bool SCALED> __device__ __forceinline__ void transpose_item_t(const float* W, int K, int N, bf16* WT, int mode, LAS float* scr, int item, int lane, const float* gvec, const float* scv, const float* shv, float* biasp) {
;     ...
; #pragma unroll
;     for (int i = 0; i < 32; ++i) scr[(2 * i + (lane >> 5)) * 33 + (lane & 31)] = tv[i];
;     asm volatile("s_waitcnt lgkmcnt(0)" ::: "memory");
;     const int c = lane & 7;
; #pragma unroll
;     for (int j = 0; j < 4; ++j) { const int n = (lane >> 3) + 8 * j; const LAS float* s = scr + (8 * c) * 33 + n;
;         v4u o; o.x = pk2(s[0 * 33], s[1 * 33]); o.y = pk2(s[2 * 33], s[3 * 33]); o.z = pk2(s[4 * 33], s[5 * 33]); o.w = pk2(s[6 * 33], s[7 * 33]);
;         *(v4u*)(WT + (size_t)(d0 + n) * K + k0 + 8 * c) = o; }
;     asm volatile("s_waitcnt lgkmcnt(0)" ::: "memory");
	ds_write2_b32 v30, v70, v71 offset0:32 offset1:98
	s_waitcnt vmcnt(12)
	ds_write2_b32 v30, v72, v73 offset0:164 offset1:230
	s_waitcnt vmcnt(10)
	ds_write2_b32 v31, v74, v75 offset0:40 offset1:106
	s_waitcnt vmcnt(8)
	ds_write2_b32 v31, v76, v52 offset0:172 offset1:238
	s_waitcnt vmcnt(6)
	ds_write2_b32 v32, v38, v39 offset0:48 offset1:114
	s_waitcnt vmcnt(4)
	ds_write2_b32 v32, v40, v41 offset0:180 offset1:246
	s_waitcnt vmcnt(2)
	ds_write2_b32 v33, v42, v43 offset0:56 offset1:122
	s_waitcnt vmcnt(0)
	ds_write2_b32 v33, v44, v36 offset0:188 offset1:254
	s_waitcnt lgkmcnt(0)
	ds_read2_b32 v[40:41], v23 offset1:8
	ds_read2_b32 v[44:45], v23 offset0:33 offset1:41
	ds_read2_b32 v[46:47], v23 offset0:66 offset1:74
	ds_read2_b32 v[48:49], v23 offset0:99 offset1:107
	ds_read2_b32 v[50:51], v23 offset0:132 offset1:140
	s_waitcnt lgkmcnt(4)
	v_bfe_u32 v36, v40, 16, 1
	v_add3_u32 v36, v40, v36, s12
	s_waitcnt lgkmcnt(3)
	v_bfe_u32 v37, v44, 16, 1
	v_lshrrev_b32_e32 v36, 16, v36
	v_add3_u32 v37, v44, v37, s12
	ds_read2_b32 v[52:53], v23 offset0:165 offset1:173
	v_and_or_b32 v36, v37, s13, v36
	s_waitcnt lgkmcnt(3)
	v_bfe_u32 v37, v46, 16, 1
	v_add3_u32 v37, v46, v37, s12
	s_waitcnt lgkmcnt(2)
	v_bfe_u32 v38, v48, 16, 1
	ds_read2_b32 v[54:55], v23 offset0:198 offset1:206
	v_lshrrev_b32_e32 v37, 16, v37
	v_add3_u32 v38, v48, v38, s12
	ds_read2_b32 v[56:57], v23 offset0:231 offset1:239
	v_and_or_b32 v37, v38, s13, v37
	s_waitcnt lgkmcnt(3)
	v_bfe_u32 v38, v50, 16, 1
	v_add3_u32 v38, v50, v38, s12
	s_waitcnt lgkmcnt(2)
	v_bfe_u32 v39, v52, 16, 1
	v_lshrrev_b32_e32 v38, 16, v38
	v_add3_u32 v39, v52, v39, s12
	v_and_or_b32 v38, v39, s13, v38
	s_waitcnt lgkmcnt(1)
	v_bfe_u32 v39, v54, 16, 1
	v_add3_u32 v39, v54, v39, s12
	s_waitcnt lgkmcnt(0)
	v_bfe_u32 v40, v56, 16, 1
	v_lshrrev_b32_e32 v39, 16, v39
	v_add3_u32 v40, v56, v40, s12
	v_lshl_add_u64 v[42:43], v[10:11], 0, s[0:1]
	v_and_or_b32 v39, v40, s13, v39
	v_add_u32_e32 v40, s4, v22
	v_mad_i64_i32 v[58:59], s[6:7], v40, s14, v[42:43]
	global_store_dwordx4 v[58:59], v[36:39], off
	v_bfe_u32 v40, v57, 16, 1
	v_add3_u32 v40, v57, v40, s12
	v_bfe_u32 v36, v41, 16, 1
	v_add3_u32 v36, v41, v36, s12
	v_bfe_u32 v37, v45, 16, 1
	v_lshrrev_b32_e32 v36, 16, v36
	v_add3_u32 v37, v45, v37, s12
	v_and_or_b32 v36, v37, s13, v36
	v_bfe_u32 v37, v47, 16, 1
	v_add3_u32 v37, v47, v37, s12
	v_bfe_u32 v38, v49, 16, 1
	v_lshrrev_b32_e32 v37, 16, v37
	v_add3_u32 v38, v49, v38, s12
	v_and_or_b32 v37, v38, s13, v37
	v_bfe_u32 v38, v51, 16, 1
	v_add3_u32 v38, v51, v38, s12
	v_bfe_u32 v39, v53, 16, 1
	v_lshrrev_b32_e32 v38, 16, v38
	v_add3_u32 v39, v53, v39, s12
	v_and_or_b32 v38, v39, s13, v38
	v_bfe_u32 v39, v55, 16, 1
	v_add3_u32 v39, v55, v39, s12
	v_lshrrev_b32_e32 v39, 16, v39
	v_add_u32_e32 v44, s4, v24
	v_and_or_b32 v39, v40, s13, v39
	ds_read2_b32 v[40:41], v23 offset0:16 offset1:24
	v_mad_i64_i32 v[44:45], s[6:7], v44, s14, v[42:43]
	global_store_dwordx4 v[44:45], v[36:39], off
	ds_read2_b32 v[44:45], v23 offset0:49 offset1:57
	ds_read2_b32 v[46:47], v23 offset0:82 offset1:90
	ds_read2_b32 v[48:49], v23 offset0:115 offset1:123
	s_waitcnt lgkmcnt(3)
	v_bfe_u32 v36, v40, 16, 1
	v_add3_u32 v36, v40, v36, s12
	s_waitcnt lgkmcnt(2)
	v_bfe_u32 v37, v44, 16, 1
	ds_read2_b32 v[50:51], v23 offset0:148 offset1:156
	v_lshrrev_b32_e32 v36, 16, v36
	v_add3_u32 v37, v44, v37, s12
	ds_read2_b32 v[52:53], v23 offset0:181 offset1:189
	v_and_or_b32 v36, v37, s13, v36
	s_waitcnt lgkmcnt(3)
	v_bfe_u32 v37, v46, 16, 1
	v_add3_u32 v37, v46, v37, s12
	s_waitcnt lgkmcnt(2)
	v_bfe_u32 v38, v48, 16, 1
	ds_read2_b32 v[54:55], v23 offset0:214 offset1:222
	v_lshrrev_b32_e32 v37, 16, v37
	v_add3_u32 v38, v48, v38, s12
	ds_read2_b32 v[56:57], v23 offset0:247 offset1:255
	v_and_or_b32 v37, v38, s13, v37
	s_waitcnt lgkmcnt(3)
	v_bfe_u32 v38, v50, 16, 1
	v_add3_u32 v38, v50, v38, s12
	s_waitcnt lgkmcnt(2)
	v_bfe_u32 v39, v52, 16, 1
	v_lshrrev_b32_e32 v38, 16, v38
	v_add3_u32 v39, v52, v39, s12
	v_and_or_b32 v38, v39, s13, v38
	s_waitcnt lgkmcnt(1)
	v_bfe_u32 v39, v54, 16, 1
	v_add3_u32 v39, v54, v39, s12
	s_waitcnt lgkmcnt(0)
	v_bfe_u32 v40, v56, 16, 1
	v_lshrrev_b32_e32 v39, 16, v39
	v_add3_u32 v40, v56, v40, s12
	v_and_or_b32 v39, v40, s13, v39
	v_add_u32_e32 v40, s4, v25
	v_mad_i64_i32 v[58:59], s[6:7], v40, s14, v[42:43]
	global_store_dwordx4 v[58:59], v[36:39], off
	v_bfe_u32 v40, v57, 16, 1
	v_add3_u32 v40, v57, v40, s12
	v_bfe_u32 v36, v41, 16, 1
	v_add3_u32 v36, v41, v36, s12
	v_bfe_u32 v37, v45, 16, 1
	v_lshrrev_b32_e32 v36, 16, v36
	v_add3_u32 v37, v45, v37, s12
	v_and_or_b32 v36, v37, s13, v36
	v_bfe_u32 v37, v47, 16, 1
	v_add3_u32 v37, v47, v37, s12
	v_bfe_u32 v38, v49, 16, 1
	v_lshrrev_b32_e32 v37, 16, v37
	v_add3_u32 v38, v49, v38, s12
	v_and_or_b32 v37, v38, s13, v37
	v_bfe_u32 v38, v51, 16, 1
	v_add3_u32 v38, v51, v38, s12
	v_bfe_u32 v39, v53, 16, 1
	v_lshrrev_b32_e32 v38, 16, v38
	v_add3_u32 v39, v53, v39, s12
	v_and_or_b32 v38, v39, s13, v38
	v_bfe_u32 v39, v55, 16, 1
	v_add3_u32 v39, v55, v39, s12
	v_lshrrev_b32_e32 v39, 16, v39
	v_and_or_b32 v39, v40, s13, v39
	v_add_u32_e32 v40, s4, v26
	v_mad_i64_i32 v[40:41], s[4:5], v40, s14, v[42:43]
	global_store_dwordx4 v[40:41], v[36:39], off
	s_waitcnt lgkmcnt(0)

; #define LAS __attribute__((address_space(3)))
; __device__ __forceinline__ void transpose_item(const float* W, int K, int N, bf16* WT, int mode, LAS float* scr, int item, int lane) { transpose_item_t<false>(W, K, N, WT, mode, scr, item, lane, nullptr, nullptr, nullptr, nullptr); }
; template <bool SCALED> __device__ __forceinline__ void transpose_item_t(const float* W, int K, int N, bf16* WT, int mode, LAS float* scr, int item, int lane, const float* gvec, const float* scv, const float* shv, float* biasp) {
;     const int nblk = N / 32, kb = item / nblk, nb = item % nblk, k0 = 64 * kb, n0 = 32 * nb, d0 = dst_row0(mode, n0);
;     float tv[32];
; #pragma unroll
;     for (int i = 0; i < 32; ++i) tv[i] = W[(size_t)(k0 + 2 * i + (lane >> 5)) * N + n0 + (lane & 31)];
; __global__ void __launch_bounds__(512, 2) hybrid_fwd(Args args) {
;     ...
;             if (r < I_4) { transpose_item(w_ffn1_out, DFF, DM, W2, 0, scr, r, lane); continue; } r -= I_4;
.LBB0_40:
	s_andn2_b64 vcc, exec, s[4:5]
	s_cbranch_vccnz .LBB0_42
	s_add_i32 s0, s10, 0x1800
	s_and_b32 s5, s0, 0x1ffc0
	s_and_b32 s4, s8, 0x3e0
	v_add_u32_e32 v36, s5, v20
	s_lshl_b32 s0, s4, 2
	v_ashrrev_i32_e32 v37, 31, v36
	v_lshl_add_u64 v[38:39], v[12:13], 0, s[0:1]
	v_lshlrev_b64 v[36:37], 12, v[36:37]
	v_lshl_add_u64 v[36:37], v[38:39], 0, v[36:37]
	v_add_co_u32_e32 v38, vcc, 0x2000, v36
	s_lshl_b32 s0, s5, 1
	s_nop 0
	v_addc_co_u32_e32 v39, vcc, 0, v37, vcc
	v_add_co_u32_e32 v40, vcc, 0x4000, v36
	s_nop 1
	v_addc_co_u32_e32 v41, vcc, 0, v37, vcc
	v_add_co_u32_e32 v42, vcc, 0x6000, v36
	s_nop 1
	v_addc_co_u32_e32 v43, vcc, 0, v37, vcc
	v_add_co_u32_e32 v44, vcc, 0x8000, v36
	s_nop 1
	v_addc_co_u32_e32 v45, vcc, 0, v37, vcc
	v_add_co_u32_e32 v46, vcc, 0xa000, v36
	s_nop 1
	v_addc_co_u32_e32 v47, vcc, 0, v37, vcc
	v_add_co_u32_e32 v48, vcc, 0xc000, v36
	s_nop 1
	v_addc_co_u32_e32 v49, vcc, 0, v37, vcc
	v_add_co_u32_e32 v50, vcc, 0xe000, v36
	s_nop 1
	v_addc_co_u32_e32 v51, vcc, 0, v37, vcc
	global_load_dword v54, v[36:37], off nt
	global_load_dword v55, v[38:39], off nt
	global_load_dword v56, v[40:41], off nt
	global_load_dword v57, v[42:43], off nt
	global_load_dword v58, v[44:45], off nt
	global_load_dword v59, v[46:47], off nt
	global_load_dword v60, v[48:49], off nt
	global_load_dword v61, v[50:51], off nt
	v_add_co_u32_e32 v38, vcc, 0x10000, v36
	s_nop 1
	v_addc_co_u32_e32 v39, vcc, 0, v37, vcc
	v_add_co_u32_e32 v40, vcc, 0x12000, v36
	s_nop 1
	v_addc_co_u32_e32 v41, vcc, 0, v37, vcc
	v_add_co_u32_e32 v42, vcc, 0x14000, v36
	s_nop 1
	v_addc_co_u32_e32 v43, vcc, 0, v37, vcc
	v_add_co_u32_e32 v44, vcc, 0x16000, v36
	s_nop 1
	v_addc_co_u32_e32 v45, vcc, 0, v37, vcc
	v_add_co_u32_e32 v46, vcc, 0x18000, v36
	s_nop 1
	v_addc_co_u32_e32 v47, vcc, 0, v37, vcc
	v_add_co_u32_e32 v48, vcc, 0x1a000, v36
	s_nop 1
	v_addc_co_u32_e32 v49, vcc, 0, v37, vcc
	v_add_co_u32_e32 v50, vcc, 0x1c000, v36
	s_nop 1
	v_addc_co_u32_e32 v51, vcc, 0, v37, vcc
	v_add_co_u32_e32 v52, vcc, 0x1e000, v36
	s_nop 1
	v_addc_co_u32_e32 v53, vcc, 0, v37, vcc
	global_load_dword v62, v[38:39], off nt
	global_load_dword v63, v[40:41], off nt
	global_load_dword v64, v[42:43], off nt
	global_load_dword v65, v[44:45], off nt
	global_load_dword v66, v[46:47], off nt
	global_load_dword v67, v[48:49], off nt
	global_load_dword v68, v[50:51], off nt
	global_load_dword v69, v[52:53], off nt
	v_add_co_u32_e32 v38, vcc, 0x20000, v36
	s_nop 1
	v_addc_co_u32_e32 v39, vcc, 0, v37, vcc
	v_add_co_u32_e32 v40, vcc, 0x22000, v36
	s_nop 1
	v_addc_co_u32_e32 v41, vcc, 0, v37, vcc
	v_add_co_u32_e32 v42, vcc, 0x24000, v36
	s_nop 1
	v_addc_co_u32_e32 v43, vcc, 0, v37, vcc
	v_add_co_u32_e32 v44, vcc, 0x26000, v36
	s_nop 1
	v_addc_co_u32_e32 v45, vcc, 0, v37, vcc
	v_add_co_u32_e32 v46, vcc, 0x28000, v36
	s_nop 1
	v_addc_co_u32_e32 v47, vcc, 0, v37, vcc
	v_add_co_u32_e32 v48, vcc, 0x2a000, v36
	s_nop 1
	v_addc_co_u32_e32 v49, vcc, 0, v37, vcc
	v_add_co_u32_e32 v50, vcc, 0x2c000, v36
	s_nop 1
	v_addc_co_u32_e32 v51, vcc, 0, v37, vcc
	v_add_co_u32_e32 v52, vcc, 0x2e000, v36
	s_nop 1
	v_addc_co_u32_e32 v53, vcc, 0, v37, vcc
	global_load_dword v70, v[38:39], off nt
	global_load_dword v71, v[40:41], off nt
	global_load_dword v72, v[42:43], off nt
	global_load_dword v73, v[44:45], off nt
	global_load_dword v74, v[46:47], off nt
	global_load_dword v75, v[48:49], off nt
	global_load_dword v76, v[50:51], off nt
	s_nop 0
	global_load_dword v52, v[52:53], off nt
	v_add_co_u32_e32 v38, vcc, 0x30000, v36
	s_nop 1
	v_addc_co_u32_e32 v39, vcc, 0, v37, vcc
	v_add_co_u32_e32 v40, vcc, 0x32000, v36
	s_nop 1
	v_addc_co_u32_e32 v41, vcc, 0, v37, vcc
	v_add_co_u32_e32 v42, vcc, 0x34000, v36
	s_nop 1
	v_addc_co_u32_e32 v43, vcc, 0, v37, vcc
	v_add_co_u32_e32 v44, vcc, 0x36000, v36
	s_nop 1
	v_addc_co_u32_e32 v45, vcc, 0, v37, vcc
	v_add_co_u32_e32 v46, vcc, 0x38000, v36
	s_nop 1
	v_addc_co_u32_e32 v47, vcc, 0, v37, vcc
	v_add_co_u32_e32 v48, vcc, 0x3a000, v36
	s_nop 1
	v_addc_co_u32_e32 v49, vcc, 0, v37, vcc
	v_add_co_u32_e32 v50, vcc, 0x3c000, v36
	s_nop 1
	v_addc_co_u32_e32 v51, vcc, 0, v37, vcc
	v_add_co_u32_e32 v36, vcc, 0x3e000, v36
	s_nop 1
	v_addc_co_u32_e32 v37, vcc, 0, v37, vcc
	global_load_dword v38, v[38:39], off nt
	s_nop 0
	global_load_dword v39, v[40:41], off nt
	s_nop 0
	global_load_dword v40, v[42:43], off nt
	global_load_dword v41, v[44:45], off nt
	s_nop 0
	global_load_dword v42, v[46:47], off nt
	global_load_dword v43, v[48:49], off nt
	global_load_dword v44, v[50:51], off nt
	s_nop 0
	global_load_dword v36, v[36:37], off nt
	s_waitcnt vmcnt(30)
	ds_write2_b32 v21, v54, v55 offset1:66
	s_waitcnt vmcnt(28)
	ds_write2_b32 v21, v56, v57 offset0:132 offset1:198
	s_waitcnt vmcnt(26)
	ds_write2_b32 v27, v58, v59 offset0:8 offset1:74
	s_waitcnt vmcnt(24)
	ds_write2_b32 v27, v60, v61 offset0:140 offset1:206
	s_waitcnt vmcnt(22)
	ds_write2_b32 v28, v62, v63 offset0:16 offset1:82
	s_waitcnt vmcnt(20)
	ds_write2_b32 v28, v64, v65 offset0:148 offset1:214
	s_waitcnt vmcnt(18)
	ds_write2_b32 v29, v66, v67 offset0:24 offset1:90
	s_waitcnt vmcnt(16)
	ds_write2_b32 v29, v68, v69 offset0:156 offset1:222
	s_waitcnt vmcnt(14)
; #define LAS __attribute__((address_space(3)))
; __device__ __forceinline__ unsigned pk2(float lo, float hi) { return f2bf(lo) | (f2bf(hi) << 16); }
; template <bool SCALED> __device__ __forceinline__ void transpose_item_t(const float* W, int K, int N, bf16* WT, int mode, LAS float* scr, int item, int lane, const float* gvec, const float* scv, const float* shv, float* biasp) {
;     ...
; #pragma unroll
;     for (int i = 0; i < 32; ++i) scr[(2 * i + (lane >> 5)) * 33 + (lane & 31)] = tv[i];
;     asm volatile("s_waitcnt lgkmcnt(0)" ::: "memory");
;     const int c = lane & 7;
; #pragma unroll
;     for (int j = 0; j < 4; ++j) { const int n = (lane >> 3) + 8 * j; const LAS float* s = scr + (8 * c) * 33 + n;
;         v4u o; o.x = pk2(s[0 * 33], s[1 * 33]); o.y = pk2(s[2 * 33], s[3 * 33]); o.z = pk2(s[4 * 33], s[5 * 33]); o.w = pk2(s[6 * 33], s[7 * 33]);
;         *(v4u*)(WT + (size_t)(d0 + n) * K + k0 + 8 * c) = o; }
;     asm volatile("s_waitcnt lgkmcnt(0)" ::: "memory");
	ds_write2_b32 v30, v70, v71 offset0:32 offset1:98
	s_waitcnt vmcnt(12)
	ds_write2_b32 v30, v72, v73 offset0:164 offset1:230
	s_waitcnt vmcnt(10)
	ds_write2_b32 v31, v74, v75 offset0:40 offset1:106
	s_waitcnt vmcnt(8)
	ds_write2_b32 v31, v76, v52 offset0:172 offset1:238
	s_waitcnt vmcnt(6)
	ds_write2_b32 v32, v38, v39 offset0:48 offset1:114
	s_waitcnt vmcnt(4)
	ds_write2_b32 v32, v40, v41 offset0:180 offset1:246
	s_waitcnt vmcnt(2)
	ds_write2_b32 v33, v42, v43 offset0:56 offset1:122
	s_waitcnt vmcnt(0)
	ds_write2_b32 v33, v44, v36 offset0:188 offset1:254
	s_waitcnt lgkmcnt(0)
	ds_read2_b32 v[40:41], v23 offset1:8
	ds_read2_b32 v[44:45], v23 offset0:33 offset1:41
	ds_read2_b32 v[46:47], v23 offset0:66 offset1:74
	ds_read2_b32 v[48:49], v23 offset0:99 offset1:107
	ds_read2_b32 v[50:51], v23 offset0:132 offset1:140
	s_waitcnt lgkmcnt(4)
	v_bfe_u32 v36, v40, 16, 1
	v_add3_u32 v36, v40, v36, s12
	s_waitcnt lgkmcnt(3)
	v_bfe_u32 v37, v44, 16, 1
	v_lshrrev_b32_e32 v36, 16, v36
	v_add3_u32 v37, v44, v37, s12
	ds_read2_b32 v[52:53], v23 offset0:165 offset1:173
	v_and_or_b32 v36, v37, s13, v36
	s_waitcnt lgkmcnt(3)
	v_bfe_u32 v37, v46, 16, 1
	v_add3_u32 v37, v46, v37, s12
	s_waitcnt lgkmcnt(2)
	v_bfe_u32 v38, v48, 16, 1
	ds_read2_b32 v[54:55], v23 offset0:198 offset1:206
	v_lshrrev_b32_e32 v37, 16, v37
	v_add3_u32 v38, v48, v38, s12
	ds_read2_b32 v[56:57], v23 offset0:231 offset1:239
	v_and_or_b32 v37, v38, s13, v37
	s_waitcnt lgkmcnt(3)
	v_bfe_u32 v38, v50, 16, 1
	v_add3_u32 v38, v50, v38, s12
	s_waitcnt lgkmcnt(2)
	v_bfe_u32 v39, v52, 16, 1
	v_lshrrev_b32_e32 v38, 16, v38
	v_add3_u32 v39, v52, v39, s12
	v_and_or_b32 v38, v39, s13, v38
	s_waitcnt lgkmcnt(1)
	v_bfe_u32 v39, v54, 16, 1
	v_add3_u32 v39, v54, v39, s12
	s_waitcnt lgkmcnt(0)
	v_bfe_u32 v40, v56, 16, 1
	v_lshrrev_b32_e32 v39, 16, v39
	v_add3_u32 v40, v56, v40, s12
	v_lshl_add_u64 v[42:43], v[14:15], 0, s[0:1]
	v_and_or_b32 v39, v40, s13, v39
	v_add_u32_e32 v40, s4, v22
	v_mad_i64_i32 v[58:59], s[6:7], v40, s14, v[42:43]
	global_store_dwordx4 v[58:59], v[36:39], off
	v_bfe_u32 v40, v57, 16, 1
	v_add3_u32 v40, v57, v40, s12
	v_bfe_u32 v36, v41, 16, 1
	v_add3_u32 v36, v41, v36, s12
	v_bfe_u32 v37, v45, 16, 1
	v_lshrrev_b32_e32 v36, 16, v36
	v_add3_u32 v37, v45, v37, s12
	v_and_or_b32 v36, v37, s13, v36
	v_bfe_u32 v37, v47, 16, 1
	v_add3_u32 v37, v47, v37, s12
	v_bfe_u32 v38, v49, 16, 1
	v_lshrrev_b32_e32 v37, 16, v37
	v_add3_u32 v38, v49, v38, s12
	v_and_or_b32 v37, v38, s13, v37
	v_bfe_u32 v38, v51, 16, 1
	v_add3_u32 v38, v51, v38, s12
	v_bfe_u32 v39, v53, 16, 1
	v_lshrrev_b32_e32 v38, 16, v38
	v_add3_u32 v39, v53, v39, s12
	v_and_or_b32 v38, v39, s13, v38
	v_bfe_u32 v39, v55, 16, 1
	v_add3_u32 v39, v55, v39, s12
	v_lshrrev_b32_e32 v39, 16, v39
	v_add_u32_e32 v44, s4, v24
	v_and_or_b32 v39, v40, s13, v39
	ds_read2_b32 v[40:41], v23 offset0:16 offset1:24
	v_mad_i64_i32 v[44:45], s[6:7], v44, s14, v[42:43]
	global_store_dwordx4 v[44:45], v[36:39], off
	ds_read2_b32 v[44:45], v23 offset0:49 offset1:57
	ds_read2_b32 v[46:47], v23 offset0:82 offset1:90
	ds_read2_b32 v[48:49], v23 offset0:115 offset1:123
	s_waitcnt lgkmcnt(3)
	v_bfe_u32 v36, v40, 16, 1
	v_add3_u32 v36, v40, v36, s12
	s_waitcnt lgkmcnt(2)
	v_bfe_u32 v37, v44, 16, 1
	ds_read2_b32 v[50:51], v23 offset0:148 offset1:156
	v_lshrrev_b32_e32 v36, 16, v36
	v_add3_u32 v37, v44, v37, s12
	ds_read2_b32 v[52:53], v23 offset0:181 offset1:189
	v_and_or_b32 v36, v37, s13, v36
	s_waitcnt lgkmcnt(3)
	v_bfe_u32 v37, v46, 16, 1
	v_add3_u32 v37, v46, v37, s12
	s_waitcnt lgkmcnt(2)
	v_bfe_u32 v38, v48, 16, 1
	ds_read2_b32 v[54:55], v23 offset0:214 offset1:222
	v_lshrrev_b32_e32 v37, 16, v37
	v_add3_u32 v38, v48, v38, s12
	ds_read2_b32 v[56:57], v23 offset0:247 offset1:255
	v_and_or_b32 v37, v38, s13, v37
	s_waitcnt lgkmcnt(3)
	v_bfe_u32 v38, v50, 16, 1
	v_add3_u32 v38, v50, v38, s12
	s_waitcnt lgkmcnt(2)
	v_bfe_u32 v39, v52, 16, 1
	v_lshrrev_b32_e32 v38, 16, v38
	v_add3_u32 v39, v52, v39, s12
	v_and_or_b32 v38, v39, s13, v38
	s_waitcnt lgkmcnt(1)
	v_bfe_u32 v39, v54, 16, 1
	v_add3_u32 v39, v54, v39, s12
	s_waitcnt lgkmcnt(0)
	v_bfe_u32 v40, v56, 16, 1
	v_lshrrev_b32_e32 v39, 16, v39
	v_add3_u32 v40, v56, v40, s12
	v_and_or_b32 v39, v40, s13, v39
	v_add_u32_e32 v40, s4, v25
	v_mad_i64_i32 v[58:59], s[6:7], v40, s14, v[42:43]
	global_store_dwordx4 v[58:59], v[36:39], off
	v_bfe_u32 v40, v57, 16, 1
	v_add3_u32 v40, v57, v40, s12
	v_bfe_u32 v36, v41, 16, 1
	v_add3_u32 v36, v41, v36, s12
	v_bfe_u32 v37, v45, 16, 1
	v_lshrrev_b32_e32 v36, 16, v36
	v_add3_u32 v37, v45, v37, s12
	v_and_or_b32 v36, v37, s13, v36
	v_bfe_u32 v37, v47, 16, 1
	v_add3_u32 v37, v47, v37, s12
	v_bfe_u32 v38, v49, 16, 1
	v_lshrrev_b32_e32 v37, 16, v37
	v_add3_u32 v38, v49, v38, s12
	v_and_or_b32 v37, v38, s13, v37
	v_bfe_u32 v38, v51, 16, 1
	v_add3_u32 v38, v51, v38, s12
	v_bfe_u32 v39, v53, 16, 1
	v_lshrrev_b32_e32 v38, 16, v38
	v_add3_u32 v39, v53, v39, s12
	v_and_or_b32 v38, v39, s13, v38
	v_bfe_u32 v39, v55, 16, 1
	v_add3_u32 v39, v55, v39, s12
	v_lshrrev_b32_e32 v39, 16, v39
	v_and_or_b32 v39, v40, s13, v39
	v_add_u32_e32 v40, s4, v26
	v_mad_i64_i32 v[40:41], s[4:5], v40, s14, v[42:43]
	global_store_dwordx4 v[40:41], v[36:39], off
	s_waitcnt lgkmcnt(0)

; #define LAS __attribute__((address_space(3)))
; __device__ __forceinline__ void transpose_item(const float* W, int K, int N, bf16* WT, int mode, LAS float* scr, int item, int lane) { transpose_item_t<false>(W, K, N, WT, mode, scr, item, lane, nullptr, nullptr, nullptr, nullptr); }
; template <bool SCALED> __device__ __forceinline__ void transpose_item_t(const float* W, int K, int N, bf16* WT, int mode, LAS float* scr, int item, int lane, const float* gvec, const float* scv, const float* shv, float* biasp) {
;     const int nblk = N / 32, kb = item / nblk, nb = item % nblk, k0 = 64 * kb, n0 = 32 * nb, d0 = dst_row0(mode, n0);
;     float tv[32];
; #pragma unroll
;     for (int i = 0; i < 32; ++i) tv[i] = W[(size_t)(k0 + 2 * i + (lane >> 5)) * N + n0 + (lane & 31)];
;     if (mode == 1) {
;         const float fsc = n0 < DFF ? 1.4426950408889634f : 0.6931471805599453f;
; #pragma unroll
;         for (int i = 0; i < 32; ++i) tv[i] *= fsc;
;     }
; __global__ void __launch_bounds__(512, 2) hybrid_fwd(Args args) {
;     ...
;         constexpr int I_1 = (DM / 64) * (NFF / 32);
;         constexpr int I_4 = (DFF / 64) * (DM / 32), I_A0 = (AW / 64) * (DM / 32), I_O0 = (DM / 64) * (DM / 32);
;         for (int it = gw; it < I_1 + 2 * I_4 + I_A0 + I_O0; it += NGW) {
;             int r = it;
;             if (r < I_1) { transpose_item(w_ffn1_in, DM, NFF, W1, 1, scr, r, lane); continue; } r -= I_1;
.LBB0_43:
	s_andn2_b64 vcc, exec, s[4:5]
	s_cbranch_vccnz .LBB0_28
	s_mul_hi_i32 s0, s16, 0x2e8ba2e9
	s_lshr_b32 s4, s0, 31
	s_ashr_i32 s0, s0, 5
	s_add_i32 s0, s0, s4
	s_mul_i32 s4, s0, 0xffffff50
	s_mul_i32 s6, s0, 0xffffea00
	s_add_i32 s5, s16, s4
	s_lshl_b32 s4, s0, 6
	s_add_i32 s6, s8, s6
	s_cmpk_gt_i32 s5, 0x57
	s_cselect_b32 s17, 0xfffff500, 0
	s_cselect_b32 s20, 0x80, 0
	v_add_u32_e32 v54, s4, v20
	s_ashr_i32 s7, s6, 31
	v_lshl_add_u64 v[36:37], s[6:7], 2, v[16:17]
	v_add_u32_e32 v40, 2, v54
	v_add_u32_e32 v42, 4, v54
	v_add_u32_e32 v44, 6, v54
	v_add_u32_e32 v46, 8, v54
	v_add_u32_e32 v48, 10, v54
	v_add_u32_e32 v50, 12, v54
	v_add_u32_e32 v52, 14, v54
	v_mad_i64_i32 v[38:39], s[18:19], v54, s15, v[36:37]
	v_mad_i64_i32 v[40:41], s[18:19], v40, s15, v[36:37]
	v_mad_i64_i32 v[42:43], s[18:19], v42, s15, v[36:37]
	v_mad_i64_i32 v[44:45], s[18:19], v44, s15, v[36:37]
	v_mad_i64_i32 v[46:47], s[18:19], v46, s15, v[36:37]
	v_mad_i64_i32 v[48:49], s[18:19], v48, s15, v[36:37]
	v_mad_i64_i32 v[50:51], s[18:19], v50, s15, v[36:37]
	v_mad_i64_i32 v[52:53], s[18:19], v52, s15, v[36:37]
	global_load_dword v55, v[38:39], off nt
	global_load_dword v56, v[40:41], off nt
	global_load_dword v57, v[42:43], off nt
	global_load_dword v58, v[44:45], off nt
	global_load_dword v59, v[46:47], off nt
	global_load_dword v60, v[48:49], off nt
	global_load_dword v61, v[50:51], off nt
	global_load_dword v62, v[52:53], off nt
	v_add_u32_e32 v38, 16, v54
	v_add_u32_e32 v40, 18, v54
	v_add_u32_e32 v42, 20, v54
	v_add_u32_e32 v44, 22, v54
	v_add_u32_e32 v46, 24, v54
	v_add_u32_e32 v48, 26, v54
	v_add_u32_e32 v50, 28, v54
	v_add_u32_e32 v52, 30, v54
	v_mad_i64_i32 v[38:39], s[18:19], v38, s15, v[36:37]
	v_mad_i64_i32 v[40:41], s[18:19], v40, s15, v[36:37]
	v_mad_i64_i32 v[42:43], s[18:19], v42, s15, v[36:37]
	v_mad_i64_i32 v[44:45], s[18:19], v44, s15, v[36:37]
	v_mad_i64_i32 v[46:47], s[18:19], v46, s15, v[36:37]
	v_mad_i64_i32 v[48:49], s[18:19], v48, s15, v[36:37]
	v_mad_i64_i32 v[50:51], s[18:19], v50, s15, v[36:37]
	v_mad_i64_i32 v[52:53], s[18:19], v52, s15, v[36:37]
	global_load_dword v63, v[38:39], off nt
	global_load_dword v64, v[40:41], off nt
	global_load_dword v65, v[42:43], off nt
	global_load_dword v66, v[44:45], off nt
	global_load_dword v67, v[46:47], off nt
	global_load_dword v68, v[48:49], off nt
	global_load_dword v69, v[50:51], off nt
	global_load_dword v70, v[52:53], off nt
	v_add_u32_e32 v38, 32, v54
	v_add_u32_e32 v40, 34, v54
	v_add_u32_e32 v42, 36, v54
	v_add_u32_e32 v44, 38, v54
	v_add_u32_e32 v46, 40, v54
	v_add_u32_e32 v48, 42, v54
	v_add_u32_e32 v50, 44, v54
	v_add_u32_e32 v52, 46, v54
	v_mad_i64_i32 v[38:39], s[18:19], v38, s15, v[36:37]
	v_mad_i64_i32 v[40:41], s[18:19], v40, s15, v[36:37]
	v_mad_i64_i32 v[42:43], s[18:19], v42, s15, v[36:37]
	v_mad_i64_i32 v[44:45], s[18:19], v44, s15, v[36:37]
	v_mad_i64_i32 v[46:47], s[18:19], v46, s15, v[36:37]
	v_mad_i64_i32 v[48:49], s[18:19], v48, s15, v[36:37]
	v_mad_i64_i32 v[50:51], s[18:19], v50, s15, v[36:37]
	v_mad_i64_i32 v[52:53], s[18:19], v52, s15, v[36:37]
	global_load_dword v71, v[38:39], off nt
	global_load_dword v72, v[40:41], off nt
	global_load_dword v73, v[42:43], off nt
	global_load_dword v74, v[44:45], off nt
	global_load_dword v75, v[46:47], off nt
	global_load_dword v76, v[48:49], off nt
	global_load_dword v77, v[50:51], off nt
	s_nop 0
	global_load_dword v52, v[52:53], off nt
	v_add_u32_e32 v38, 48, v54
	v_add_u32_e32 v40, 50, v54
	v_add_u32_e32 v42, 52, v54
	v_add_u32_e32 v44, 54, v54
	v_add_u32_e32 v46, 56, v54
	v_add_u32_e32 v48, 58, v54
	v_add_u32_e32 v50, 60, v54
	v_add_u32_e32 v53, 62, v54
	v_mad_i64_i32 v[38:39], s[18:19], v38, s15, v[36:37]
	v_mad_i64_i32 v[40:41], s[18:19], v40, s15, v[36:37]
	v_mad_i64_i32 v[42:43], s[18:19], v42, s15, v[36:37]
	v_mad_i64_i32 v[44:45], s[18:19], v44, s15, v[36:37]
	v_mad_i64_i32 v[46:47], s[18:19], v46, s15, v[36:37]
	v_mad_i64_i32 v[48:49], s[18:19], v48, s15, v[36:37]
	v_mad_i64_i32 v[50:51], s[18:19], v50, s15, v[36:37]
	v_mad_i64_i32 v[36:37], s[18:19], v53, s15, v[36:37]
	global_load_dword v38, v[38:39], off nt
	s_nop 0
	global_load_dword v39, v[40:41], off nt
	s_nop 0
	global_load_dword v40, v[42:43], off nt
	global_load_dword v41, v[44:45], off nt
	s_nop 0
	global_load_dword v42, v[46:47], off nt
	global_load_dword v43, v[48:49], off nt
	global_load_dword v44, v[50:51], off nt
	s_nop 0
	global_load_dword v36, v[36:37], off nt
	s_mulk_i32 s0, 0x1600
	s_sub_i32 s0, s17, s0
	s_add_i32 s0, s8, s0
	s_lshl_b32 s0, s0, 1
	s_and_b32 s6, s6, 0x60
	s_and_b32 s0, s0, 0xffffff00
	s_or_b32 s6, s20, s6
	s_or_b32 s0, s6, s0
	s_cmpk_lt_i32 s5, 0x58
	s_cselect_b64 vcc, -1, 0
	v_cndmask_b32_e32 v37, v34, v35, vcc
	s_waitcnt vmcnt(31)
	v_mul_f32_e32 v45, v37, v55
	s_waitcnt vmcnt(30)
	v_mul_f32_e32 v46, v37, v56
	s_waitcnt vmcnt(29)
	v_mul_f32_e32 v47, v37, v57
	s_waitcnt vmcnt(28)
	v_mul_f32_e32 v48, v37, v58
	s_waitcnt vmcnt(27)
	v_mul_f32_e32 v49, v37, v59
	s_waitcnt vmcnt(26)
	v_mul_f32_e32 v50, v37, v60
	s_waitcnt vmcnt(25)
	v_mul_f32_e32 v51, v37, v61
	s_waitcnt vmcnt(24)
	v_mul_f32_e32 v53, v37, v62
	s_ashr_i32 s5, s4, 31
	s_waitcnt vmcnt(23)
	v_mul_f32_e32 v54, v37, v63
	s_waitcnt vmcnt(22)
	v_mul_f32_e32 v55, v37, v64
	s_waitcnt vmcnt(21)
	v_mul_f32_e32 v56, v37, v65
	s_waitcnt vmcnt(20)
	v_mul_f32_e32 v57, v37, v66
	s_waitcnt vmcnt(19)
	v_mul_f32_e32 v58, v37, v67
	s_waitcnt vmcnt(18)
	v_mul_f32_e32 v59, v37, v68
	s_waitcnt vmcnt(17)
	v_mul_f32_e32 v60, v37, v69
	s_waitcnt vmcnt(16)
	v_mul_f32_e32 v61, v37, v70
	s_waitcnt vmcnt(15)
	v_mul_f32_e32 v62, v37, v71
	s_waitcnt vmcnt(14)
	v_mul_f32_e32 v63, v37, v72
	s_waitcnt vmcnt(13)
; #define LAS __attribute__((address_space(3)))
; __device__ __forceinline__ unsigned pk2(float lo, float hi) { return f2bf(lo) | (f2bf(hi) << 16); }
; template <bool SCALED> __device__ __forceinline__ void transpose_item_t(const float* W, int K, int N, bf16* WT, int mode, LAS float* scr, int item, int lane, const float* gvec, const float* scv, const float* shv, float* biasp) {
;     ...
;         for (int i = 0; i < 32; ++i) tv[i] *= fsc;
;     }
;     if (SCALED) {
;         float part = 0.f;
; #pragma unroll
;         for (int i = 0; i < 32; ++i) { const int k = k0 + 2 * i + (lane >> 5); part += tv[i] * shv[k]; tv[i] *= gvec[k] * (1.0f + scv[k]); }
;         part += __shfl_xor(part, 32);
;         if (lane < 32) biasp[(size_t)kb * NBIAS + d0 + lane] = part;
;     }
; #pragma unroll
;     for (int i = 0; i < 32; ++i) scr[(2 * i + (lane >> 5)) * 33 + (lane & 31)] = tv[i];
;     asm volatile("s_waitcnt lgkmcnt(0)" ::: "memory");
;     const int c = lane & 7;
; #pragma unroll
;     for (int j = 0; j < 4; ++j) { const int n = (lane >> 3) + 8 * j; const LAS float* s = scr + (8 * c) * 33 + n;
;         v4u o; o.x = pk2(s[0 * 33], s[1 * 33]); o.y = pk2(s[2 * 33], s[3 * 33]); o.z = pk2(s[4 * 33], s[5 * 33]); o.w = pk2(s[6 * 33], s[7 * 33]);
;         *(v4u*)(WT + (size_t)(d0 + n) * K + k0 + 8 * c) = o; }
;     asm volatile("s_waitcnt lgkmcnt(0)" ::: "memory");
	v_mul_f32_e32 v64, v37, v73
	s_waitcnt vmcnt(12)
	v_mul_f32_e32 v65, v37, v74
	s_waitcnt vmcnt(11)
	v_mul_f32_e32 v66, v37, v75
	s_waitcnt vmcnt(10)
	v_mul_f32_e32 v67, v37, v76
	s_waitcnt vmcnt(9)
	v_mul_f32_e32 v68, v37, v77
	s_waitcnt vmcnt(8)
	v_mul_f32_e32 v52, v37, v52
	s_waitcnt vmcnt(7)
	v_mul_f32_e32 v38, v37, v38
	s_waitcnt vmcnt(6)
	v_mul_f32_e32 v39, v37, v39
	s_waitcnt vmcnt(5)
	v_mul_f32_e32 v40, v37, v40
	s_waitcnt vmcnt(4)
	v_mul_f32_e32 v41, v37, v41
	s_waitcnt vmcnt(3)
	v_mul_f32_e32 v42, v37, v42
	s_waitcnt vmcnt(2)
	v_mul_f32_e32 v43, v37, v43
	s_waitcnt vmcnt(1)
	v_mul_f32_e32 v44, v37, v44
	s_waitcnt vmcnt(0)
	v_mul_f32_e32 v36, v37, v36
	ds_write2_b32 v21, v45, v46 offset1:66
	ds_write2_b32 v21, v47, v48 offset0:132 offset1:198
	ds_write2_b32 v27, v49, v50 offset0:8 offset1:74
	ds_write2_b32 v27, v51, v53 offset0:140 offset1:206
	ds_write2_b32 v28, v54, v55 offset0:16 offset1:82
	ds_write2_b32 v28, v56, v57 offset0:148 offset1:214
	ds_write2_b32 v29, v58, v59 offset0:24 offset1:90
	ds_write2_b32 v29, v60, v61 offset0:156 offset1:222
	ds_write2_b32 v30, v62, v63 offset0:32 offset1:98
	ds_write2_b32 v30, v64, v65 offset0:164 offset1:230
	ds_write2_b32 v31, v66, v67 offset0:40 offset1:106
	ds_write2_b32 v31, v68, v52 offset0:172 offset1:238
	ds_write2_b32 v32, v38, v39 offset0:48 offset1:114
	ds_write2_b32 v32, v40, v41 offset0:180 offset1:246
	ds_write2_b32 v33, v42, v43 offset0:56 offset1:122
	ds_write2_b32 v33, v44, v36 offset0:188 offset1:254
	s_waitcnt lgkmcnt(0)
	ds_read2_b32 v[40:41], v23 offset1:8
	ds_read2_b32 v[44:45], v23 offset0:33 offset1:41
	ds_read2_b32 v[46:47], v23 offset0:66 offset1:74
	ds_read2_b32 v[48:49], v23 offset0:99 offset1:107
	ds_read2_b32 v[50:51], v23 offset0:132 offset1:140
	s_waitcnt lgkmcnt(4)
	v_bfe_u32 v36, v40, 16, 1
	v_add3_u32 v36, v40, v36, s12
	s_waitcnt lgkmcnt(3)
	v_bfe_u32 v37, v44, 16, 1
	v_lshrrev_b32_e32 v36, 16, v36
	v_add3_u32 v37, v44, v37, s12
	ds_read2_b32 v[52:53], v23 offset0:165 offset1:173
	v_and_or_b32 v36, v37, s13, v36
	s_waitcnt lgkmcnt(3)
	v_bfe_u32 v37, v46, 16, 1
	v_add3_u32 v37, v46, v37, s12
	s_waitcnt lgkmcnt(2)
	v_bfe_u32 v38, v48, 16, 1
	ds_read2_b32 v[54:55], v23 offset0:198 offset1:206
	v_lshrrev_b32_e32 v37, 16, v37
	v_add3_u32 v38, v48, v38, s12
	ds_read2_b32 v[56:57], v23 offset0:231 offset1:239
	v_and_or_b32 v37, v38, s13, v37
	s_waitcnt lgkmcnt(3)
	v_bfe_u32 v38, v50, 16, 1
	v_add3_u32 v38, v50, v38, s12
	s_waitcnt lgkmcnt(2)
	v_bfe_u32 v39, v52, 16, 1
	v_lshrrev_b32_e32 v38, 16, v38
	v_add3_u32 v39, v52, v39, s12
	v_and_or_b32 v38, v39, s13, v38
	s_waitcnt lgkmcnt(1)
	v_bfe_u32 v39, v54, 16, 1
	v_add_u32_e32 v58, s0, v22
	v_add3_u32 v39, v54, v39, s12
	s_waitcnt lgkmcnt(0)
	v_bfe_u32 v40, v56, 16, 1
	v_ashrrev_i32_e32 v59, 31, v58
	v_lshl_add_u64 v[42:43], s[4:5], 1, v[18:19]
	v_lshrrev_b32_e32 v39, 16, v39
	v_add3_u32 v40, v56, v40, s12
	v_lshlrev_b64 v[58:59], 11, v[58:59]
	v_and_or_b32 v39, v40, s13, v39
	v_lshl_add_u64 v[58:59], v[42:43], 0, v[58:59]
	global_store_dwordx4 v[58:59], v[36:39], off
	v_bfe_u32 v40, v57, 16, 1
	v_add3_u32 v40, v57, v40, s12
	v_bfe_u32 v36, v41, 16, 1
	v_add3_u32 v36, v41, v36, s12
	v_bfe_u32 v37, v45, 16, 1
	v_lshrrev_b32_e32 v36, 16, v36
	v_add3_u32 v37, v45, v37, s12
	v_and_or_b32 v36, v37, s13, v36
	v_bfe_u32 v37, v47, 16, 1
	v_add3_u32 v37, v47, v37, s12
	v_bfe_u32 v38, v49, 16, 1
	v_lshrrev_b32_e32 v37, 16, v37
	v_add3_u32 v38, v49, v38, s12
	v_and_or_b32 v37, v38, s13, v37
	v_bfe_u32 v38, v51, 16, 1
	v_add3_u32 v38, v51, v38, s12
	v_bfe_u32 v39, v53, 16, 1
	v_lshrrev_b32_e32 v38, 16, v38
	v_add3_u32 v39, v53, v39, s12
	v_and_or_b32 v38, v39, s13, v38
	v_bfe_u32 v39, v55, 16, 1
	v_add3_u32 v39, v55, v39, s12
	v_lshrrev_b32_e32 v39, 16, v39
	v_and_or_b32 v39, v40, s13, v39
	v_add_u32_e32 v40, s0, v24
	v_ashrrev_i32_e32 v41, 31, v40
	v_lshlrev_b64 v[40:41], 11, v[40:41]
	ds_read2_b32 v[44:45], v23 offset0:16 offset1:24
	v_lshl_add_u64 v[40:41], v[42:43], 0, v[40:41]
	global_store_dwordx4 v[40:41], v[36:39], off
	ds_read2_b32 v[40:41], v23 offset0:49 offset1:57
	ds_read2_b32 v[46:47], v23 offset0:82 offset1:90
	ds_read2_b32 v[48:49], v23 offset0:115 offset1:123
	s_waitcnt lgkmcnt(3)
	v_bfe_u32 v36, v44, 16, 1
	v_add3_u32 v36, v44, v36, s12
	s_waitcnt lgkmcnt(2)
	v_bfe_u32 v37, v40, 16, 1
	ds_read2_b32 v[50:51], v23 offset0:148 offset1:156
	v_lshrrev_b32_e32 v36, 16, v36
	v_add3_u32 v37, v40, v37, s12
	ds_read2_b32 v[52:53], v23 offset0:181 offset1:189
	v_and_or_b32 v36, v37, s13, v36
	s_waitcnt lgkmcnt(3)
	v_bfe_u32 v37, v46, 16, 1
	v_add3_u32 v37, v46, v37, s12
	s_waitcnt lgkmcnt(2)
	v_bfe_u32 v38, v48, 16, 1
	ds_read2_b32 v[54:55], v23 offset0:214 offset1:222
	v_lshrrev_b32_e32 v37, 16, v37
	v_add3_u32 v38, v48, v38, s12
	ds_read2_b32 v[56:57], v23 offset0:247 offset1:255
	v_and_or_b32 v37, v38, s13, v37
	s_waitcnt lgkmcnt(3)
	v_bfe_u32 v38, v50, 16, 1
	v_add3_u32 v38, v50, v38, s12
	s_waitcnt lgkmcnt(2)
	v_bfe_u32 v39, v52, 16, 1
	v_lshrrev_b32_e32 v38, 16, v38
	v_add3_u32 v39, v52, v39, s12
	v_and_or_b32 v38, v39, s13, v38
	s_waitcnt lgkmcnt(1)
	v_bfe_u32 v39, v54, 16, 1
	v_add_u32_e32 v58, s0, v25
	v_add3_u32 v39, v54, v39, s12
	s_waitcnt lgkmcnt(0)
	v_bfe_u32 v40, v56, 16, 1
	v_ashrrev_i32_e32 v59, 31, v58
	v_lshrrev_b32_e32 v39, 16, v39
	v_add3_u32 v40, v56, v40, s12
	v_lshlrev_b64 v[58:59], 11, v[58:59]
	v_and_or_b32 v39, v40, s13, v39
	v_lshl_add_u64 v[58:59], v[42:43], 0, v[58:59]
	global_store_dwordx4 v[58:59], v[36:39], off
	v_bfe_u32 v40, v57, 16, 1
	v_add3_u32 v40, v57, v40, s12
	v_bfe_u32 v36, v45, 16, 1
	v_add3_u32 v36, v45, v36, s12
	v_bfe_u32 v37, v41, 16, 1
	v_lshrrev_b32_e32 v36, 16, v36
	v_add3_u32 v37, v41, v37, s12
	v_and_or_b32 v36, v37, s13, v36
	v_bfe_u32 v37, v47, 16, 1
	v_add3_u32 v37, v47, v37, s12
	v_bfe_u32 v38, v49, 16, 1
	v_lshrrev_b32_e32 v37, 16, v37
	v_add3_u32 v38, v49, v38, s12
	v_and_or_b32 v37, v38, s13, v37
	v_bfe_u32 v38, v51, 16, 1
	v_add3_u32 v38, v51, v38, s12
	v_bfe_u32 v39, v53, 16, 1
	v_lshrrev_b32_e32 v38, 16, v38
	v_add3_u32 v39, v53, v39, s12
	v_and_or_b32 v38, v39, s13, v38
	v_bfe_u32 v39, v55, 16, 1
	v_add3_u32 v39, v55, v39, s12
	v_lshrrev_b32_e32 v39, 16, v39
	v_and_or_b32 v39, v40, s13, v39
	v_add_u32_e32 v40, s0, v26
	v_ashrrev_i32_e32 v41, 31, v40
	v_lshlrev_b64 v[40:41], 11, v[40:41]
	v_lshl_add_u64 v[40:41], v[42:43], 0, v[40:41]
	global_store_dwordx4 v[40:41], v[36:39], off
	s_waitcnt lgkmcnt(0)
	s_branch .LBB0_28

; __device__ __forceinline__ float silu_f(float a) { return a / (1.f + __expf(-a)); }
; __global__ void __launch_bounds__(512, 2) hybrid_fwd(Args args) {
;     ...
;         for (int cb = blk; cb < 256; cb += G) {
;             const int c4 = lane & 15, ks = lane >> 4;
;             f32x4 a0 = {0.f, 0.f, 0.f, 0.f}, a1 = {0.f, 0.f, 0.f, 0.f};
;             if (c4 < 9) {
;                 const int j = 36 * cb + 4 * c4, kbase = wave * 128 + ks * 32;
; #pragma unroll 8
;                 for (int i = 0; i < 32; ++i) { const int k = kbase + i; const f32x4 wv = *(const f32x4*)(w_ada + (size_t)k * NADA + j);
;                     a0 += wv * silu_f(cvec[k]); a1 += wv * silu_f(cvec[DM + k]); }
.LBB0_54:
	v_lshlrev_b32_e32 v0, 2, v226
	v_add_u32_e32 v1, 0x1000, v0
	global_load_dword v2, v0, s[62:63]
	global_load_dword v3, v0, s[62:63] offset:2048
	global_load_dword v4, v1, s[62:63]
	global_load_dword v5, v1, s[62:63] offset:2048
	s_mul_i32 s0, s91, 0x480000
	s_mul_i32 s1, s59, 0x90
	s_add_u32 s0, s0, s1
	s_add_u32 s0, s64, s0
	s_addc_u32 s1, s65, 0
	v_lshrrev_b32_e32 v6, 4, v160
	v_and_b32_e32 v7, 15, v160
	v_mul_u32_u24_e32 v6, 0x120000, v6
	v_lshl_add_u32 v6, v7, 4, v6
	v_mov_b32_e32 v58, 0
	v_mov_b32_e32 v59, 0
	v_mov_b32_e32 v60, 0
	v_mov_b32_e32 v61, 0
	v_mov_b32_e32 v62, 0
	v_mov_b32_e32 v63, 0
	v_mov_b32_e32 v64, 0
	v_mov_b32_e32 v65, 0
	s_and_saveexec_b64 s[54:55], s[4:5]
	s_lshl_b32 s3, s91, 2
	s_mul_i32 s10, s3, 0x9000
	s_add_u32 s0, s0, s10
	s_addc_u32 s1, s1, 0
	global_load_dwordx4 v[80:83], v6, s[0:1] nt
	s_add_u32 s0, s0, 0x9000
	s_addc_u32 s1, s1, 0
	s_add_i32 s3, s3, 1
	s_cmp_eq_u32 s3, 32
	s_cselect_b32 s10, 0x120000, 0
	s_cselect_b32 s3, 0, s3
	s_sub_u32 s0, s0, s10
	s_subb_u32 s1, s1, 0
	global_load_dwordx4 v[84:87], v6, s[0:1] nt
	s_add_u32 s0, s0, 0x9000
	s_addc_u32 s1, s1, 0
	s_add_i32 s3, s3, 1
	s_cmp_eq_u32 s3, 32
	s_cselect_b32 s10, 0x120000, 0
	s_cselect_b32 s3, 0, s3
	s_sub_u32 s0, s0, s10
	s_subb_u32 s1, s1, 0
	global_load_dwordx4 v[88:91], v6, s[0:1] nt
	s_add_u32 s0, s0, 0x9000
	s_addc_u32 s1, s1, 0
	s_add_i32 s3, s3, 1
	s_cmp_eq_u32 s3, 32
	s_cselect_b32 s10, 0x120000, 0
	s_cselect_b32 s3, 0, s3
	s_sub_u32 s0, s0, s10
	s_subb_u32 s1, s1, 0
	global_load_dwordx4 v[92:95], v6, s[0:1] nt
	s_add_u32 s0, s0, 0x9000
	s_addc_u32 s1, s1, 0
	s_add_i32 s3, s3, 1
	s_cmp_eq_u32 s3, 32
	s_cselect_b32 s10, 0x120000, 0
	s_cselect_b32 s3, 0, s3
	s_sub_u32 s0, s0, s10
	s_subb_u32 s1, s1, 0
	global_load_dwordx4 v[96:99], v6, s[0:1] nt
	s_add_u32 s0, s0, 0x9000
	s_addc_u32 s1, s1, 0
	s_add_i32 s3, s3, 1
	s_cmp_eq_u32 s3, 32
	s_cselect_b32 s10, 0x120000, 0
	s_cselect_b32 s3, 0, s3
	s_sub_u32 s0, s0, s10
	s_subb_u32 s1, s1, 0
	global_load_dwordx4 v[100:103], v6, s[0:1] nt
	s_add_u32 s0, s0, 0x9000
	s_addc_u32 s1, s1, 0
	s_add_i32 s3, s3, 1
	s_cmp_eq_u32 s3, 32
	s_cselect_b32 s10, 0x120000, 0
	s_cselect_b32 s3, 0, s3
	s_sub_u32 s0, s0, s10
	s_subb_u32 s1, s1, 0
	global_load_dwordx4 v[104:107], v6, s[0:1] nt
	s_add_u32 s0, s0, 0x9000
	s_addc_u32 s1, s1, 0
	s_add_i32 s3, s3, 1
	s_cmp_eq_u32 s3, 32
	s_cselect_b32 s10, 0x120000, 0
	s_cselect_b32 s3, 0, s3
	s_sub_u32 s0, s0, s10
	s_subb_u32 s1, s1, 0
	global_load_dwordx4 v[108:111], v6, s[0:1] nt
	s_add_u32 s0, s0, 0x9000
	s_addc_u32 s1, s1, 0
	s_add_i32 s3, s3, 1
	s_cmp_eq_u32 s3, 32
	s_cselect_b32 s10, 0x120000, 0
	s_cselect_b32 s3, 0, s3
	s_sub_u32 s0, s0, s10
	s_subb_u32 s1, s1, 0
	global_load_dwordx4 v[112:115], v6, s[0:1] nt
	s_add_u32 s0, s0, 0x9000
	s_addc_u32 s1, s1, 0
	s_add_i32 s3, s3, 1
	s_cmp_eq_u32 s3, 32
	s_cselect_b32 s10, 0x120000, 0
	s_cselect_b32 s3, 0, s3
	s_sub_u32 s0, s0, s10
	s_subb_u32 s1, s1, 0
	global_load_dwordx4 v[116:119], v6, s[0:1] nt
	s_add_u32 s0, s0, 0x9000
	s_addc_u32 s1, s1, 0
	s_add_i32 s3, s3, 1
	s_cmp_eq_u32 s3, 32
	s_cselect_b32 s10, 0x120000, 0
	s_cselect_b32 s3, 0, s3
	s_sub_u32 s0, s0, s10
	s_subb_u32 s1, s1, 0
	global_load_dwordx4 v[120:123], v6, s[0:1] nt
	s_add_u32 s0, s0, 0x9000
	s_addc_u32 s1, s1, 0
	s_add_i32 s3, s3, 1
	s_cmp_eq_u32 s3, 32
	s_cselect_b32 s10, 0x120000, 0
	s_cselect_b32 s3, 0, s3
	s_sub_u32 s0, s0, s10
	s_subb_u32 s1, s1, 0
	global_load_dwordx4 v[124:127], v6, s[0:1] nt
	s_add_u32 s0, s0, 0x9000
	s_addc_u32 s1, s1, 0
	s_add_i32 s3, s3, 1
	s_cmp_eq_u32 s3, 32
	s_cselect_b32 s10, 0x120000, 0
	s_cselect_b32 s3, 0, s3
	s_sub_u32 s0, s0, s10
	s_subb_u32 s1, s1, 0
	global_load_dwordx4 v[128:131], v6, s[0:1] nt
	s_add_u32 s0, s0, 0x9000
	s_addc_u32 s1, s1, 0
	s_add_i32 s3, s3, 1
	s_cmp_eq_u32 s3, 32
	s_cselect_b32 s10, 0x120000, 0
	s_cselect_b32 s3, 0, s3
	s_sub_u32 s0, s0, s10
	s_subb_u32 s1, s1, 0
	global_load_dwordx4 v[132:135], v6, s[0:1] nt
	s_add_u32 s0, s0, 0x9000
	s_addc_u32 s1, s1, 0
	s_add_i32 s3, s3, 1
	s_cmp_eq_u32 s3, 32
	s_cselect_b32 s10, 0x120000, 0
	s_cselect_b32 s3, 0, s3
	s_sub_u32 s0, s0, s10
	s_subb_u32 s1, s1, 0
	global_load_dwordx4 v[136:139], v6, s[0:1] nt
	s_add_u32 s0, s0, 0x9000
	s_addc_u32 s1, s1, 0
	s_add_i32 s3, s3, 1
	s_cmp_eq_u32 s3, 32
	s_cselect_b32 s10, 0x120000, 0
	s_cselect_b32 s3, 0, s3
	s_sub_u32 s0, s0, s10
	s_subb_u32 s1, s1, 0
	global_load_dwordx4 v[140:143], v6, s[0:1] nt
	s_add_u32 s0, s0, 0x9000
	s_addc_u32 s1, s1, 0
	s_add_i32 s3, s3, 1
	s_cmp_eq_u32 s3, 32
	s_cselect_b32 s10, 0x120000, 0
	s_cselect_b32 s3, 0, s3
	s_sub_u32 s0, s0, s10
	s_subb_u32 s1, s1, 0
	global_load_dwordx4 v[144:147], v6, s[0:1] nt
	s_add_u32 s0, s0, 0x9000
	s_addc_u32 s1, s1, 0
	s_add_i32 s3, s3, 1
	s_cmp_eq_u32 s3, 32
	s_cselect_b32 s10, 0x120000, 0
	s_cselect_b32 s3, 0, s3
	s_sub_u32 s0, s0, s10
	s_subb_u32 s1, s1, 0
	global_load_dwordx4 v[148:151], v6, s[0:1] nt
	s_add_u32 s0, s0, 0x9000
	s_addc_u32 s1, s1, 0
	s_add_i32 s3, s3, 1
	s_cmp_eq_u32 s3, 32
	s_cselect_b32 s10, 0x120000, 0
	s_cselect_b32 s3, 0, s3
	s_sub_u32 s0, s0, s10
	s_subb_u32 s1, s1, 0
	global_load_dwordx4 v[152:155], v6, s[0:1] nt
	s_add_u32 s0, s0, 0x9000
	s_addc_u32 s1, s1, 0
	s_add_i32 s3, s3, 1
	s_cmp_eq_u32 s3, 32
	s_cselect_b32 s10, 0x120000, 0
	s_cselect_b32 s3, 0, s3
	s_sub_u32 s0, s0, s10
	s_subb_u32 s1, s1, 0
	global_load_dwordx4 v[156:159], v6, s[0:1] nt
	s_add_u32 s0, s0, 0x9000
	s_addc_u32 s1, s1, 0
	s_add_i32 s3, s3, 1
	s_cmp_eq_u32 s3, 32
	s_cselect_b32 s10, 0x120000, 0
	s_cselect_b32 s3, 0, s3
	s_sub_u32 s0, s0, s10
	s_subb_u32 s1, s1, 0
	global_load_dwordx4 v[164:167], v6, s[0:1] nt
	s_add_u32 s0, s0, 0x9000
; __device__ __forceinline__ float silu_f(float a) { return a / (1.f + __expf(-a)); }
; __global__ void __launch_bounds__(512, 2) hybrid_fwd(Args args) {
;     ...
;                 for (int i = 0; i < 32; ++i) { const int k = kbase + i; const f32x4 wv = *(const f32x4*)(w_ada + (size_t)k * NADA + j);
;                     a0 += wv * silu_f(cvec[k]); a1 += wv * silu_f(cvec[DM + k]); }
	s_addc_u32 s1, s1, 0
	s_add_i32 s3, s3, 1
	s_cmp_eq_u32 s3, 32
	s_cselect_b32 s10, 0x120000, 0
	s_cselect_b32 s3, 0, s3
	s_sub_u32 s0, s0, s10
	s_subb_u32 s1, s1, 0
	global_load_dwordx4 v[168:171], v6, s[0:1] nt
	s_add_u32 s0, s0, 0x9000
	s_addc_u32 s1, s1, 0
	s_add_i32 s3, s3, 1
	s_cmp_eq_u32 s3, 32
	s_cselect_b32 s10, 0x120000, 0
	s_cselect_b32 s3, 0, s3
	s_sub_u32 s0, s0, s10
	s_subb_u32 s1, s1, 0
	global_load_dwordx4 v[172:175], v6, s[0:1] nt
	s_add_u32 s0, s0, 0x9000
	s_addc_u32 s1, s1, 0
	s_add_i32 s3, s3, 1
	s_cmp_eq_u32 s3, 32
	s_cselect_b32 s10, 0x120000, 0
	s_cselect_b32 s3, 0, s3
	s_sub_u32 s0, s0, s10
	s_subb_u32 s1, s1, 0
	global_load_dwordx4 v[176:179], v6, s[0:1] nt
	s_add_u32 s0, s0, 0x9000
	s_addc_u32 s1, s1, 0
	s_add_i32 s3, s3, 1
	s_cmp_eq_u32 s3, 32
	s_cselect_b32 s10, 0x120000, 0
	s_cselect_b32 s3, 0, s3
	s_sub_u32 s0, s0, s10
	s_subb_u32 s1, s1, 0
	global_load_dwordx4 v[180:183], v6, s[0:1] nt
	s_add_u32 s0, s0, 0x9000
	s_addc_u32 s1, s1, 0
	s_add_i32 s3, s3, 1
	s_cmp_eq_u32 s3, 32
	s_cselect_b32 s10, 0x120000, 0
	s_cselect_b32 s3, 0, s3
	s_sub_u32 s0, s0, s10
	s_subb_u32 s1, s1, 0
	global_load_dwordx4 v[184:187], v6, s[0:1] nt
	s_add_u32 s0, s0, 0x9000
	s_addc_u32 s1, s1, 0
	s_add_i32 s3, s3, 1
	s_cmp_eq_u32 s3, 32
	s_cselect_b32 s10, 0x120000, 0
	s_cselect_b32 s3, 0, s3
	s_sub_u32 s0, s0, s10
	s_subb_u32 s1, s1, 0
	global_load_dwordx4 v[188:191], v6, s[0:1] nt
	s_add_u32 s0, s0, 0x9000
	s_addc_u32 s1, s1, 0
	s_add_i32 s3, s3, 1
	s_cmp_eq_u32 s3, 32
	s_cselect_b32 s10, 0x120000, 0
	s_cselect_b32 s3, 0, s3
	s_sub_u32 s0, s0, s10
	s_subb_u32 s1, s1, 0
	global_load_dwordx4 v[192:195], v6, s[0:1] nt
	s_add_u32 s0, s0, 0x9000
	s_addc_u32 s1, s1, 0
	s_add_i32 s3, s3, 1
	s_cmp_eq_u32 s3, 32
	s_cselect_b32 s10, 0x120000, 0
	s_cselect_b32 s3, 0, s3
	s_sub_u32 s0, s0, s10
	s_subb_u32 s1, s1, 0
	global_load_dwordx4 v[196:199], v6, s[0:1] nt
	s_add_u32 s0, s0, 0x9000
	s_addc_u32 s1, s1, 0
	s_add_i32 s3, s3, 1
	s_cmp_eq_u32 s3, 32
	s_cselect_b32 s10, 0x120000, 0
	s_cselect_b32 s3, 0, s3
	s_sub_u32 s0, s0, s10
	s_subb_u32 s1, s1, 0
	global_load_dwordx4 v[200:203], v6, s[0:1] nt
	s_add_u32 s0, s0, 0x9000
	s_addc_u32 s1, s1, 0
	s_add_i32 s3, s3, 1
	s_cmp_eq_u32 s3, 32
	s_cselect_b32 s10, 0x120000, 0
	s_cselect_b32 s3, 0, s3
	s_sub_u32 s0, s0, s10
	s_subb_u32 s1, s1, 0
	global_load_dwordx4 v[204:207], v6, s[0:1] nt
	s_add_u32 s0, s0, 0x9000
	s_addc_u32 s1, s1, 0
	s_add_i32 s3, s3, 1
	s_cmp_eq_u32 s3, 32
	s_cselect_b32 s10, 0x120000, 0
	s_cselect_b32 s3, 0, s3
	s_sub_u32 s0, s0, s10
	s_subb_u32 s1, s1, 0
	global_load_dwordx4 v[208:211], v6, s[0:1] nt
	s_or_b64 exec, exec, s[54:55]
	s_waitcnt vmcnt(32)
	v_mul_f32_e32 v8, 0xbfb8aa3b, v2
	v_mul_f32_e32 v16, 0xbfb8aa3b, v3
	v_mul_f32_e32 v24, 0xbfb8aa3b, v4
	v_mul_f32_e32 v32, 0xbfb8aa3b, v5
	v_exp_f32_e32 v8, v8
	v_exp_f32_e32 v16, v16
	v_exp_f32_e32 v24, v24
	v_exp_f32_e32 v32, v32
	s_nop 0
	v_add_f32_e32 v9, 1.0, v8
	v_add_f32_e32 v17, 1.0, v16
	v_add_f32_e32 v25, 1.0, v24
	v_add_f32_e32 v33, 1.0, v32
	v_div_scale_f32 v10, s[10:11], v9, v9, v2
	v_div_scale_f32 v18, s[10:11], v17, v17, v3
	v_div_scale_f32 v26, s[10:11], v25, v25, v4
	v_div_scale_f32 v34, s[10:11], v33, v33, v5
	v_rcp_f32_e32 v11, v10
	v_rcp_f32_e32 v19, v18
	v_rcp_f32_e32 v27, v26
	v_rcp_f32_e32 v35, v34
	s_nop 0
	v_fma_f32 v12, -v10, v11, 1.0
	v_fma_f32 v20, -v18, v19, 1.0
	v_fma_f32 v28, -v26, v27, 1.0
	v_fma_f32 v36, -v34, v35, 1.0
	v_fmac_f32_e32 v11, v12, v11
	v_fmac_f32_e32 v19, v20, v19
	v_fmac_f32_e32 v27, v28, v27
	v_fmac_f32_e32 v35, v36, v35
	v_div_scale_f32 v13, vcc, v2, v9, v2
	v_mul_f32_e32 v14, v13, v11
	v_fma_f32 v12, -v10, v14, v13
	v_fmac_f32_e32 v14, v12, v11
	v_fma_f32 v12, -v10, v14, v13
	s_nop 0
	v_div_fmas_f32 v12, v12, v11, v14
	v_div_fixup_f32 v2, v12, v9, v2
	v_div_scale_f32 v21, vcc, v3, v17, v3
	v_mul_f32_e32 v22, v21, v19
	v_fma_f32 v20, -v18, v22, v21
	v_fmac_f32_e32 v22, v20, v19
	v_fma_f32 v20, -v18, v22, v21
	s_nop 0
	v_div_fmas_f32 v20, v20, v19, v22
	v_div_fixup_f32 v3, v20, v17, v3
	v_div_scale_f32 v29, vcc, v4, v25, v4
	v_mul_f32_e32 v30, v29, v27
	v_fma_f32 v28, -v26, v30, v29
	v_fmac_f32_e32 v30, v28, v27
	v_fma_f32 v28, -v26, v30, v29
	s_nop 0
	v_div_fmas_f32 v28, v28, v27, v30
	v_div_fixup_f32 v4, v28, v25, v4
	v_div_scale_f32 v37, vcc, v5, v33, v5
	v_mul_f32_e32 v38, v37, v35
	v_fma_f32 v36, -v34, v38, v37
	v_fmac_f32_e32 v38, v36, v35
	v_fma_f32 v36, -v34, v38, v37
	s_nop 0
	v_div_fmas_f32 v36, v36, v35, v38
	v_div_fixup_f32 v5, v36, v33, v5
	v_add_u32_e32 v0, 0x20800, v0
	ds_write_b32 v0, v2
	ds_write_b32 v0, v3 offset:2048
	ds_write_b32 v0, v4 offset:4096
	ds_write_b32 v0, v5 offset:6144
	s_waitcnt lgkmcnt(0)
	s_barrier
	s_and_saveexec_b64 s[54:55], s[4:5]
	s_cbranch_execz .LBB0_57
; __device__ __forceinline__ float silu_f(float a) { return a / (1.f + __expf(-a)); }
; __global__ void __launch_bounds__(512, 2) hybrid_fwd(Args args) {
;     ...
;             if (c4 < 9) {
;                 const int j = 36 * cb + 4 * c4, kbase = wave * 128 + ks * 32;
; #pragma unroll 8
;                 for (int i = 0; i < 32; ++i) { const int k = kbase + i; const f32x4 wv = *(const f32x4*)(w_ada + (size_t)k * NADA + j);
;                     a0 += wv * silu_f(cvec[k]); a1 += wv * silu_f(cvec[DM + k]); }
	v_lshrrev_b32_e32 v7, 4, v160
	s_lshl_b32 s0, s91, 9
	v_lshl_add_u32 v7, v7, 7, s0
	v_add_u32_e32 v7, 0x20800, v7
	s_add_i32 s10, s91, 1
	s_and_b32 s10, s10, 7
	s_lshl_b32 s10, s10, 4
	v_add_u32_e32 v6, s10, v7
	ds_read_b128 v[8:11], v6
	ds_read_b128 v[40:43], v6 offset:4096
	s_add_i32 s10, s91, 2
	s_and_b32 s10, s10, 7
	s_lshl_b32 s10, s10, 4
	v_add_u32_e32 v6, s10, v7
	ds_read_b128 v[12:15], v6
	ds_read_b128 v[44:47], v6 offset:4096
	s_add_i32 s10, s91, 3
	s_and_b32 s10, s10, 7
	s_lshl_b32 s10, s10, 4
	v_add_u32_e32 v6, s10, v7
	ds_read_b128 v[16:19], v6
	ds_read_b128 v[212:215], v6 offset:4096
	s_add_i32 s10, s91, 4
	s_and_b32 s10, s10, 7
	s_lshl_b32 s10, s10, 4
	v_add_u32_e32 v6, s10, v7
	ds_read_b128 v[20:23], v6
	ds_read_b128 v[216:219], v6 offset:4096
	s_add_i32 s10, s91, 5
	s_and_b32 s10, s10, 7
	s_lshl_b32 s10, s10, 4
	v_add_u32_e32 v6, s10, v7
	ds_read_b128 v[24:27], v6
	ds_read_b128 v[220:223], v6 offset:4096
	s_add_i32 s10, s91, 6
	s_and_b32 s10, s10, 7
	s_lshl_b32 s10, s10, 4
	v_add_u32_e32 v6, s10, v7
	ds_read_b128 v[28:31], v6
	ds_read_b128 v[228:231], v6 offset:4096
	s_add_i32 s10, s91, 7
	s_and_b32 s10, s10, 7
	s_lshl_b32 s10, s10, 4
	v_add_u32_e32 v6, s10, v7
	ds_read_b128 v[32:35], v6
	ds_read_b128 v[232:235], v6 offset:4096
	s_add_i32 s10, s91, 0
	s_and_b32 s10, s10, 7
	s_lshl_b32 s10, s10, 4
	v_add_u32_e32 v6, s10, v7
	ds_read_b128 v[0:3], v6
	ds_read_b128 v[36:39], v6 offset:4096
	s_waitcnt lgkmcnt(0)
	s_waitcnt vmcnt(31)
	v_pk_fma_f32 v[62:63], v[80:81], v[0:1], v[62:63] op_sel_hi:[1,0,1]
	v_pk_fma_f32 v[60:61], v[82:83], v[0:1], v[60:61] op_sel_hi:[1,0,1]
	v_pk_fma_f32 v[64:65], v[80:81], v[36:37], v[64:65] op_sel_hi:[1,0,1]
	v_pk_fma_f32 v[58:59], v[82:83], v[36:37], v[58:59] op_sel_hi:[1,0,1]
	s_waitcnt vmcnt(30)
	v_pk_fma_f32 v[62:63], v[84:85], v[0:1], v[62:63] op_sel:[0,1,0] op_sel_hi:[1,1,1]
	v_pk_fma_f32 v[60:61], v[86:87], v[0:1], v[60:61] op_sel:[0,1,0] op_sel_hi:[1,1,1]
	v_pk_fma_f32 v[64:65], v[84:85], v[36:37], v[64:65] op_sel:[0,1,0] op_sel_hi:[1,1,1]
	v_pk_fma_f32 v[58:59], v[86:87], v[36:37], v[58:59] op_sel:[0,1,0] op_sel_hi:[1,1,1]
	s_waitcnt vmcnt(29)
	v_pk_fma_f32 v[62:63], v[88:89], v[2:3], v[62:63] op_sel_hi:[1,0,1]
	v_pk_fma_f32 v[60:61], v[90:91], v[2:3], v[60:61] op_sel_hi:[1,0,1]
	v_pk_fma_f32 v[64:65], v[88:89], v[38:39], v[64:65] op_sel_hi:[1,0,1]
	v_pk_fma_f32 v[58:59], v[90:91], v[38:39], v[58:59] op_sel_hi:[1,0,1]
	s_waitcnt vmcnt(28)
	v_pk_fma_f32 v[62:63], v[92:93], v[2:3], v[62:63] op_sel:[0,1,0] op_sel_hi:[1,1,1]
	v_pk_fma_f32 v[60:61], v[94:95], v[2:3], v[60:61] op_sel:[0,1,0] op_sel_hi:[1,1,1]
	v_pk_fma_f32 v[64:65], v[92:93], v[38:39], v[64:65] op_sel:[0,1,0] op_sel_hi:[1,1,1]
	v_pk_fma_f32 v[58:59], v[94:95], v[38:39], v[58:59] op_sel:[0,1,0] op_sel_hi:[1,1,1]
	s_waitcnt vmcnt(27)
	v_pk_fma_f32 v[62:63], v[96:97], v[8:9], v[62:63] op_sel_hi:[1,0,1]
	v_pk_fma_f32 v[60:61], v[98:99], v[8:9], v[60:61] op_sel_hi:[1,0,1]
	v_pk_fma_f32 v[64:65], v[96:97], v[40:41], v[64:65] op_sel_hi:[1,0,1]
	v_pk_fma_f32 v[58:59], v[98:99], v[40:41], v[58:59] op_sel_hi:[1,0,1]
	s_waitcnt vmcnt(26)
	v_pk_fma_f32 v[62:63], v[100:101], v[8:9], v[62:63] op_sel:[0,1,0] op_sel_hi:[1,1,1]
	v_pk_fma_f32 v[60:61], v[102:103], v[8:9], v[60:61] op_sel:[0,1,0] op_sel_hi:[1,1,1]
	v_pk_fma_f32 v[64:65], v[100:101], v[40:41], v[64:65] op_sel:[0,1,0] op_sel_hi:[1,1,1]
	v_pk_fma_f32 v[58:59], v[102:103], v[40:41], v[58:59] op_sel:[0,1,0] op_sel_hi:[1,1,1]
	s_waitcnt vmcnt(25)
	v_pk_fma_f32 v[62:63], v[104:105], v[10:11], v[62:63] op_sel_hi:[1,0,1]
	v_pk_fma_f32 v[60:61], v[106:107], v[10:11], v[60:61] op_sel_hi:[1,0,1]
	v_pk_fma_f32 v[64:65], v[104:105], v[42:43], v[64:65] op_sel_hi:[1,0,1]
	v_pk_fma_f32 v[58:59], v[106:107], v[42:43], v[58:59] op_sel_hi:[1,0,1]
	s_waitcnt vmcnt(24)
	v_pk_fma_f32 v[62:63], v[108:109], v[10:11], v[62:63] op_sel:[0,1,0] op_sel_hi:[1,1,1]
	v_pk_fma_f32 v[60:61], v[110:111], v[10:11], v[60:61] op_sel:[0,1,0] op_sel_hi:[1,1,1]
	v_pk_fma_f32 v[64:65], v[108:109], v[42:43], v[64:65] op_sel:[0,1,0] op_sel_hi:[1,1,1]
	v_pk_fma_f32 v[58:59], v[110:111], v[42:43], v[58:59] op_sel:[0,1,0] op_sel_hi:[1,1,1]
	s_waitcnt vmcnt(23)
	v_pk_fma_f32 v[62:63], v[112:113], v[12:13], v[62:63] op_sel_hi:[1,0,1]
	v_pk_fma_f32 v[60:61], v[114:115], v[12:13], v[60:61] op_sel_hi:[1,0,1]
	v_pk_fma_f32 v[64:65], v[112:113], v[44:45], v[64:65] op_sel_hi:[1,0,1]
	v_pk_fma_f32 v[58:59], v[114:115], v[44:45], v[58:59] op_sel_hi:[1,0,1]
	s_waitcnt vmcnt(22)
	v_pk_fma_f32 v[62:63], v[116:117], v[12:13], v[62:63] op_sel:[0,1,0] op_sel_hi:[1,1,1]
	v_pk_fma_f32 v[60:61], v[118:119], v[12:13], v[60:61] op_sel:[0,1,0] op_sel_hi:[1,1,1]
	v_pk_fma_f32 v[64:65], v[116:117], v[44:45], v[64:65] op_sel:[0,1,0] op_sel_hi:[1,1,1]
	v_pk_fma_f32 v[58:59], v[118:119], v[44:45], v[58:59] op_sel:[0,1,0] op_sel_hi:[1,1,1]
	s_waitcnt vmcnt(21)
	v_pk_fma_f32 v[62:63], v[120:121], v[14:15], v[62:63] op_sel_hi:[1,0,1]
	v_pk_fma_f32 v[60:61], v[122:123], v[14:15], v[60:61] op_sel_hi:[1,0,1]
	v_pk_fma_f32 v[64:65], v[120:121], v[46:47], v[64:65] op_sel_hi:[1,0,1]
	v_pk_fma_f32 v[58:59], v[122:123], v[46:47], v[58:59] op_sel_hi:[1,0,1]
	s_waitcnt vmcnt(20)
	v_pk_fma_f32 v[62:63], v[124:125], v[14:15], v[62:63] op_sel:[0,1,0] op_sel_hi:[1,1,1]
	v_pk_fma_f32 v[60:61], v[126:127], v[14:15], v[60:61] op_sel:[0,1,0] op_sel_hi:[1,1,1]
	v_pk_fma_f32 v[64:65], v[124:125], v[46:47], v[64:65] op_sel:[0,1,0] op_sel_hi:[1,1,1]
	v_pk_fma_f32 v[58:59], v[126:127], v[46:47], v[58:59] op_sel:[0,1,0] op_sel_hi:[1,1,1]
	s_waitcnt vmcnt(19)
; __device__ __forceinline__ float silu_f(float a) { return a / (1.f + __expf(-a)); }
; __global__ void __launch_bounds__(512, 2) hybrid_fwd(Args args) {
;     ...
;                 for (int i = 0; i < 32; ++i) { const int k = kbase + i; const f32x4 wv = *(const f32x4*)(w_ada + (size_t)k * NADA + j);
;                     a0 += wv * silu_f(cvec[k]); a1 += wv * silu_f(cvec[DM + k]); }
	v_pk_fma_f32 v[62:63], v[128:129], v[16:17], v[62:63] op_sel_hi:[1,0,1]
	v_pk_fma_f32 v[60:61], v[130:131], v[16:17], v[60:61] op_sel_hi:[1,0,1]
	v_pk_fma_f32 v[64:65], v[128:129], v[212:213], v[64:65] op_sel_hi:[1,0,1]
	v_pk_fma_f32 v[58:59], v[130:131], v[212:213], v[58:59] op_sel_hi:[1,0,1]
	s_waitcnt vmcnt(18)
	v_pk_fma_f32 v[62:63], v[132:133], v[16:17], v[62:63] op_sel:[0,1,0] op_sel_hi:[1,1,1]
	v_pk_fma_f32 v[60:61], v[134:135], v[16:17], v[60:61] op_sel:[0,1,0] op_sel_hi:[1,1,1]
	v_pk_fma_f32 v[64:65], v[132:133], v[212:213], v[64:65] op_sel:[0,1,0] op_sel_hi:[1,1,1]
	v_pk_fma_f32 v[58:59], v[134:135], v[212:213], v[58:59] op_sel:[0,1,0] op_sel_hi:[1,1,1]
	s_waitcnt vmcnt(17)
	v_pk_fma_f32 v[62:63], v[136:137], v[18:19], v[62:63] op_sel_hi:[1,0,1]
	v_pk_fma_f32 v[60:61], v[138:139], v[18:19], v[60:61] op_sel_hi:[1,0,1]
	v_pk_fma_f32 v[64:65], v[136:137], v[214:215], v[64:65] op_sel_hi:[1,0,1]
	v_pk_fma_f32 v[58:59], v[138:139], v[214:215], v[58:59] op_sel_hi:[1,0,1]
	s_waitcnt vmcnt(16)
	v_pk_fma_f32 v[62:63], v[140:141], v[18:19], v[62:63] op_sel:[0,1,0] op_sel_hi:[1,1,1]
	v_pk_fma_f32 v[60:61], v[142:143], v[18:19], v[60:61] op_sel:[0,1,0] op_sel_hi:[1,1,1]
	v_pk_fma_f32 v[64:65], v[140:141], v[214:215], v[64:65] op_sel:[0,1,0] op_sel_hi:[1,1,1]
	v_pk_fma_f32 v[58:59], v[142:143], v[214:215], v[58:59] op_sel:[0,1,0] op_sel_hi:[1,1,1]
	s_waitcnt vmcnt(15)
	v_pk_fma_f32 v[62:63], v[144:145], v[20:21], v[62:63] op_sel_hi:[1,0,1]
	v_pk_fma_f32 v[60:61], v[146:147], v[20:21], v[60:61] op_sel_hi:[1,0,1]
	v_pk_fma_f32 v[64:65], v[144:145], v[216:217], v[64:65] op_sel_hi:[1,0,1]
	v_pk_fma_f32 v[58:59], v[146:147], v[216:217], v[58:59] op_sel_hi:[1,0,1]
	s_waitcnt vmcnt(14)
	v_pk_fma_f32 v[62:63], v[148:149], v[20:21], v[62:63] op_sel:[0,1,0] op_sel_hi:[1,1,1]
	v_pk_fma_f32 v[60:61], v[150:151], v[20:21], v[60:61] op_sel:[0,1,0] op_sel_hi:[1,1,1]
	v_pk_fma_f32 v[64:65], v[148:149], v[216:217], v[64:65] op_sel:[0,1,0] op_sel_hi:[1,1,1]
	v_pk_fma_f32 v[58:59], v[150:151], v[216:217], v[58:59] op_sel:[0,1,0] op_sel_hi:[1,1,1]
	s_waitcnt vmcnt(13)
	v_pk_fma_f32 v[62:63], v[152:153], v[22:23], v[62:63] op_sel_hi:[1,0,1]
	v_pk_fma_f32 v[60:61], v[154:155], v[22:23], v[60:61] op_sel_hi:[1,0,1]
	v_pk_fma_f32 v[64:65], v[152:153], v[218:219], v[64:65] op_sel_hi:[1,0,1]
	v_pk_fma_f32 v[58:59], v[154:155], v[218:219], v[58:59] op_sel_hi:[1,0,1]
	s_waitcnt vmcnt(12)
	v_pk_fma_f32 v[62:63], v[156:157], v[22:23], v[62:63] op_sel:[0,1,0] op_sel_hi:[1,1,1]
	v_pk_fma_f32 v[60:61], v[158:159], v[22:23], v[60:61] op_sel:[0,1,0] op_sel_hi:[1,1,1]
	v_pk_fma_f32 v[64:65], v[156:157], v[218:219], v[64:65] op_sel:[0,1,0] op_sel_hi:[1,1,1]
	v_pk_fma_f32 v[58:59], v[158:159], v[218:219], v[58:59] op_sel:[0,1,0] op_sel_hi:[1,1,1]
	s_waitcnt vmcnt(11)
	v_pk_fma_f32 v[62:63], v[164:165], v[24:25], v[62:63] op_sel_hi:[1,0,1]
	v_pk_fma_f32 v[60:61], v[166:167], v[24:25], v[60:61] op_sel_hi:[1,0,1]
	v_pk_fma_f32 v[64:65], v[164:165], v[220:221], v[64:65] op_sel_hi:[1,0,1]
	v_pk_fma_f32 v[58:59], v[166:167], v[220:221], v[58:59] op_sel_hi:[1,0,1]
	s_waitcnt vmcnt(10)
	v_pk_fma_f32 v[62:63], v[168:169], v[24:25], v[62:63] op_sel:[0,1,0] op_sel_hi:[1,1,1]
	v_pk_fma_f32 v[60:61], v[170:171], v[24:25], v[60:61] op_sel:[0,1,0] op_sel_hi:[1,1,1]
	v_pk_fma_f32 v[64:65], v[168:169], v[220:221], v[64:65] op_sel:[0,1,0] op_sel_hi:[1,1,1]
	v_pk_fma_f32 v[58:59], v[170:171], v[220:221], v[58:59] op_sel:[0,1,0] op_sel_hi:[1,1,1]
	s_waitcnt vmcnt(9)
	v_pk_fma_f32 v[62:63], v[172:173], v[26:27], v[62:63] op_sel_hi:[1,0,1]
	v_pk_fma_f32 v[60:61], v[174:175], v[26:27], v[60:61] op_sel_hi:[1,0,1]
	v_pk_fma_f32 v[64:65], v[172:173], v[222:223], v[64:65] op_sel_hi:[1,0,1]
	v_pk_fma_f32 v[58:59], v[174:175], v[222:223], v[58:59] op_sel_hi:[1,0,1]
	s_waitcnt vmcnt(8)
	v_pk_fma_f32 v[62:63], v[176:177], v[26:27], v[62:63] op_sel:[0,1,0] op_sel_hi:[1,1,1]
	v_pk_fma_f32 v[60:61], v[178:179], v[26:27], v[60:61] op_sel:[0,1,0] op_sel_hi:[1,1,1]
	v_pk_fma_f32 v[64:65], v[176:177], v[222:223], v[64:65] op_sel:[0,1,0] op_sel_hi:[1,1,1]
	v_pk_fma_f32 v[58:59], v[178:179], v[222:223], v[58:59] op_sel:[0,1,0] op_sel_hi:[1,1,1]
	s_waitcnt vmcnt(7)
	v_pk_fma_f32 v[62:63], v[180:181], v[28:29], v[62:63] op_sel_hi:[1,0,1]
	v_pk_fma_f32 v[60:61], v[182:183], v[28:29], v[60:61] op_sel_hi:[1,0,1]
	v_pk_fma_f32 v[64:65], v[180:181], v[228:229], v[64:65] op_sel_hi:[1,0,1]
	v_pk_fma_f32 v[58:59], v[182:183], v[228:229], v[58:59] op_sel_hi:[1,0,1]
	s_waitcnt vmcnt(6)
	v_pk_fma_f32 v[62:63], v[184:185], v[28:29], v[62:63] op_sel:[0,1,0] op_sel_hi:[1,1,1]
	v_pk_fma_f32 v[60:61], v[186:187], v[28:29], v[60:61] op_sel:[0,1,0] op_sel_hi:[1,1,1]
	v_pk_fma_f32 v[64:65], v[184:185], v[228:229], v[64:65] op_sel:[0,1,0] op_sel_hi:[1,1,1]
	v_pk_fma_f32 v[58:59], v[186:187], v[228:229], v[58:59] op_sel:[0,1,0] op_sel_hi:[1,1,1]
	s_waitcnt vmcnt(5)
	v_pk_fma_f32 v[62:63], v[188:189], v[30:31], v[62:63] op_sel_hi:[1,0,1]
	v_pk_fma_f32 v[60:61], v[190:191], v[30:31], v[60:61] op_sel_hi:[1,0,1]
	v_pk_fma_f32 v[64:65], v[188:189], v[230:231], v[64:65] op_sel_hi:[1,0,1]
	v_pk_fma_f32 v[58:59], v[190:191], v[230:231], v[58:59] op_sel_hi:[1,0,1]
	s_waitcnt vmcnt(4)
	v_pk_fma_f32 v[62:63], v[192:193], v[30:31], v[62:63] op_sel:[0,1,0] op_sel_hi:[1,1,1]
	v_pk_fma_f32 v[60:61], v[194:195], v[30:31], v[60:61] op_sel:[0,1,0] op_sel_hi:[1,1,1]
	v_pk_fma_f32 v[64:65], v[192:193], v[230:231], v[64:65] op_sel:[0,1,0] op_sel_hi:[1,1,1]
	v_pk_fma_f32 v[58:59], v[194:195], v[230:231], v[58:59] op_sel:[0,1,0] op_sel_hi:[1,1,1]
	s_waitcnt vmcnt(3)
	v_pk_fma_f32 v[62:63], v[196:197], v[32:33], v[62:63] op_sel_hi:[1,0,1]
	v_pk_fma_f32 v[60:61], v[198:199], v[32:33], v[60:61] op_sel_hi:[1,0,1]
	v_pk_fma_f32 v[64:65], v[196:197], v[232:233], v[64:65] op_sel_hi:[1,0,1]
	v_pk_fma_f32 v[58:59], v[198:199], v[232:233], v[58:59] op_sel_hi:[1,0,1]
	s_waitcnt vmcnt(2)
	v_pk_fma_f32 v[62:63], v[200:201], v[32:33], v[62:63] op_sel:[0,1,0] op_sel_hi:[1,1,1]
	v_pk_fma_f32 v[60:61], v[202:203], v[32:33], v[60:61] op_sel:[0,1,0] op_sel_hi:[1,1,1]
	v_pk_fma_f32 v[64:65], v[200:201], v[232:233], v[64:65] op_sel:[0,1,0] op_sel_hi:[1,1,1]
	v_pk_fma_f32 v[58:59], v[202:203], v[232:233], v[58:59] op_sel:[0,1,0] op_sel_hi:[1,1,1]
	s_waitcnt vmcnt(1)
	v_pk_fma_f32 v[62:63], v[204:205], v[34:35], v[62:63] op_sel_hi:[1,0,1]
	v_pk_fma_f32 v[60:61], v[206:207], v[34:35], v[60:61] op_sel_hi:[1,0,1]
	v_pk_fma_f32 v[64:65], v[204:205], v[234:235], v[64:65] op_sel_hi:[1,0,1]
	v_pk_fma_f32 v[58:59], v[206:207], v[234:235], v[58:59] op_sel_hi:[1,0,1]
	s_waitcnt vmcnt(0)
	v_pk_fma_f32 v[62:63], v[208:209], v[34:35], v[62:63] op_sel:[0,1,0] op_sel_hi:[1,1,1]
	v_pk_fma_f32 v[60:61], v[210:211], v[34:35], v[60:61] op_sel:[0,1,0] op_sel_hi:[1,1,1]
	v_pk_fma_f32 v[64:65], v[208:209], v[234:235], v[64:65] op_sel:[0,1,0] op_sel_hi:[1,1,1]
	v_pk_fma_f32 v[58:59], v[210:211], v[234:235], v[58:59] op_sel:[0,1,0] op_sel_hi:[1,1,1]

; #define OPQ(v) asm volatile("" : "+v"(v))
; __device__ __forceinline__ void norm_row(const float* xrow, bf16* orow, const float* g, const float* sh, const float* sc, int lane) {
;     const f32x4* xr = (const f32x4*)xrow + lane;
;     f32x4 v[4]; float s = 0.f;
; #pragma unroll
;     for (int j = 0; j < 4; ++j) { v[j] = xr[64 * j]; s += (v[j].x * v[j].x + v[j].y * v[j].y) + (v[j].z * v[j].z + v[j].w * v[j].w); }
;     const float rs = 1.0f / sqrtf(wave_sum(s) * (1.f / DM) + 1e-6f);
; __global__ void __launch_bounds__(512, 2) hybrid_fwd(Args args) {
;     ...
;     if (IN(1)) { OPQ(lane);
;         for (int m = gw; m < M; m += NGW) { const float* mb = mod + (m >> 13) * NADA; norm_row(x + (size_t)m * DM, XN + (size_t)m * DM, g_ffn1, mb + 0 * DM, mb + 1 * DM, lane); }
.LBB0_121:
	s_cmp_lt_i32 s82, 2
	s_cselect_b64 s[0:1], -1, 0
	s_add_u32 s28, s86, 0x2700000
	s_addc_u32 s29, s87, 0
	s_add_u32 s6, s86, 0xe800000
	s_addc_u32 s7, s87, 0
	s_and_b64 s[12:13], s[0:1], s[12:13]
	s_andn2_b64 vcc, exec, s[12:13]
	s_mov_b32 s96, s91
	s_cbranch_vccnz .LBB0_130
	s_cmpk_gt_i32 s94, 0x3fff
	v_ashrrev_i32_e32 v161, 31, v160
	s_cbranch_scc1 .LBB0_125
	v_mbcnt_lo_u32_b32 v0, -1, 0
	v_mbcnt_hi_u32_b32 v0, -1, v0
	v_and_b32_e32 v1, 64, v0
	v_add_u32_e32 v1, 64, v1
	v_xor_b32_e32 v2, 1, v0
	v_cmp_lt_i32_e32 vcc, v2, v1
	s_mov_b32 s14, s95
	s_ashr_i32 s95, s94, 31
	v_cndmask_b32_e32 v2, v0, v2, vcc
	v_lshlrev_b32_e32 v10, 2, v2
	v_xor_b32_e32 v2, 2, v0
	v_cmp_lt_i32_e32 vcc, v2, v1
	s_lshl_b64 s[0:1], s[94:95], 11
	s_add_u32 s0, s86, s0
	v_cndmask_b32_e32 v2, v0, v2, vcc
	v_lshlrev_b32_e32 v11, 2, v2
	v_xor_b32_e32 v2, 4, v0
	v_cmp_lt_i32_e32 vcc, v2, v1
	s_addc_u32 s1, s87, s1
	s_ashr_i32 s91, s90, 31
	v_cndmask_b32_e32 v2, v0, v2, vcc
	v_lshlrev_b32_e32 v12, 2, v2
	v_xor_b32_e32 v2, 8, v0
	v_cmp_lt_i32_e32 vcc, v2, v1
	s_lshl_b64 s[4:5], s[90:91], 11
	v_mov_b32_e32 v16, 0x358637bd
	v_cndmask_b32_e32 v2, v0, v2, vcc
	v_lshlrev_b32_e32 v13, 2, v2
	v_xor_b32_e32 v2, 16, v0
	v_cmp_lt_i32_e32 vcc, v2, v1
	s_mov_b32 s3, 0xf800000
	v_mov_b32_e32 v17, 0x260
	v_cndmask_b32_e32 v2, v0, v2, vcc
	v_lshlrev_b32_e32 v14, 2, v2
	v_xor_b32_e32 v2, 32, v0
	v_cmp_lt_i32_e32 vcc, v2, v1
	s_mov_b64 s[16:17], 0x1000
	s_movk_i32 s18, 0x1000
	v_cndmask_b32_e32 v0, v0, v2, vcc
	v_lshl_add_u64 v[2:3], v[160:161], 3, s[0:1]
	s_mov_b64 s[0:1], 0x4300600
	v_lshl_add_u64 v[6:7], v[2:3], 0, s[0:1]
	s_lshl_b64 s[0:1], s[94:95], 12
	s_waitcnt lgkmcnt(0)
	s_add_u32 s0, s60, s0
	v_lshlrev_b32_e32 v15, 2, v0
	v_lshlrev_b64 v[0:1], 4, v[160:161]
	s_addc_u32 s1, s61, s1
	v_lshl_add_u64 v[4:5], s[68:69], 0, v[0:1]
	v_lshl_add_u64 v[0:1], s[0:1], 0, v[0:1]
	s_mov_b64 s[0:1], 0x800
	s_mov_b32 s95, s14
	v_lshl_add_u64 v[8:9], v[0:1], 0, s[0:1]
	s_lshl_b64 s[14:15], s[90:91], 12
	s_movk_i32 s19, 0x7fff
	s_mov_b32 s20, 0xffff0000
	s_mov_b32 s21, s94
	s_mov_b32 s98, -1
	global_load_dwordx4 v[64:67], v[4:5], off
	global_load_dwordx4 v[68:71], v[4:5], off offset:1024
	global_load_dwordx4 v[72:75], v[4:5], off offset:2048
	global_load_dwordx4 v[76:79], v[4:5], off offset:3072
	global_load_dwordx4 v[112:115], v[8:9], off offset:-2048 nt
	global_load_dwordx4 v[116:119], v[8:9], off offset:-1024 nt
	global_load_dwordx4 v[120:123], v[8:9], off nt
	global_load_dwordx4 v[124:127], v[8:9], off offset:1024 nt

; __device__ __forceinline__ void norm_row(const float* xrow, bf16* orow, const float* g, const float* sh, const float* sc, int lane) {
;     const f32x4* xr = (const f32x4*)xrow + lane;
;     f32x4 v[4]; float s = 0.f;
; #pragma unroll
;     for (int j = 0; j < 4; ++j) { v[j] = xr[64 * j]; s += (v[j].x * v[j].x + v[j].y * v[j].y) + (v[j].z * v[j].z + v[j].w * v[j].w); }
; __global__ void __launch_bounds__(512, 2) hybrid_fwd(Args args) {
;     ...
;         for (int m = gw; m < M; m += NGW) { const float* mb = mod + (m >> 13) * NADA; norm_row(x + (size_t)m * DM, XN + (size_t)m * DM, g_ffn1, mb + 0 * DM, mb + 1 * DM, lane); }
.Lnorm_same:
	s_waitcnt vmcnt(4)
	v_mov_b32_e32 v18, v112
	v_mov_b32_e32 v19, v113
	v_mov_b32_e32 v20, v114
	v_mov_b32_e32 v21, v115
	v_mov_b32_e32 v22, v116
	v_mov_b32_e32 v23, v117
	v_mov_b32_e32 v24, v118
	v_mov_b32_e32 v25, v119
	v_mov_b32_e32 v26, v120
	v_mov_b32_e32 v27, v121
	v_mov_b32_e32 v28, v122
	v_mov_b32_e32 v29, v123
	v_mov_b32_e32 v0, v124
	v_mov_b32_e32 v1, v125
	v_mov_b32_e32 v2, v126
	v_mov_b32_e32 v3, v127
	s_add_i32 s21, s21, s90
	v_lshl_add_u64 v[8:9], v[8:9], 0, s[14:15]
	s_cmpk_gt_i32 s21, 0x3fff
	s_cbranch_scc1 .Lnorm_nopf
	global_load_dwordx4 v[112:115], v[8:9], off offset:-2048 nt
	global_load_dwordx4 v[116:119], v[8:9], off offset:-1024 nt
	global_load_dwordx4 v[120:123], v[8:9], off nt
	global_load_dwordx4 v[124:127], v[8:9], off offset:1024 nt

; #define LAS __attribute__((address_space(3)))
; template <bool SCALED> __device__ __forceinline__ void transpose_item_t(const float* W, int K, int N, bf16* WT, int mode, LAS float* scr, int item, int lane, const float* gvec, const float* scv, const float* shv, float* biasp) {
;     const int nblk = N / 32, kb = item / nblk, nb = item % nblk, k0 = 64 * kb, n0 = 32 * nb, d0 = dst_row0(mode, n0);
;     float tv[32];
; #pragma unroll
;     for (int i = 0; i < 32; ++i) tv[i] = W[(size_t)(k0 + 2 * i + (lane >> 5)) * N + n0 + (lane & 31)];
;     if (mode == 1) {
;         const float fsc = n0 < DFF ? 1.4426950408889634f : 0.6931471805599453f;
; #pragma unroll
;         for (int i = 0; i < 32; ++i) tv[i] *= fsc;
;     }
;     if (SCALED) {
;         float part = 0.f;
; #pragma unroll
;         for (int i = 0; i < 32; ++i) { const int k = k0 + 2 * i + (lane >> 5); part += tv[i] * shv[k]; tv[i] *= gvec[k] * (1.0f + scv[k]); }
; __global__ void __launch_bounds__(512, 2) hybrid_fwd(Args args) {
;     ...
;         for (int it = gw; it < 2 * I_1; it += NGW) { const int bb = it >= I_1 ? 1 : 0; const float* mb = mod + bb * NADA;
;             transpose_item_t<true>(w_ffn2_in, DM, NFF, W3 + (size_t)bb * NFF * DM, 1, scr, it - bb * I_1, lane, g_ffn2, mb + 7 * DM, mb + 6 * DM, BIASP + (size_t)bb * 16 * NBIAS + NIN); }
.LBB0_128:
	s_cmpk_gt_i32 s94, 0xaff
	s_cselect_b64 s[18:19], -1, 0
	s_and_b64 s[16:17], s[18:19], exec
	s_cselect_b32 s16, 0x9000, 0
	s_cselect_b32 s17, 0xfffff500, 0
	s_add_u32 s24, s22, s16
	s_addc_u32 s25, s23, 0
	s_add_i32 s16, s17, s94
	s_mul_hi_i32 s17, s16, 0x2e8ba2e9
	s_lshr_b32 s20, s17, 31
	s_ashr_i32 s17, s17, 5
	s_add_i32 s17, s17, s20
	s_mul_i32 s20, s17, 0xb0
	s_sub_i32 s31, s16, s20
	s_lshl_b32 s16, s17, 6
	s_lshl_b32 s20, s31, 5
	s_cmpk_gt_i32 s31, 0x57
	s_cselect_b32 s35, 0xfffff500, 0
	s_cselect_b32 s34, 0x80, 0
	v_add_u32_e32 v4, s16, v10
	s_ashr_i32 s21, s20, 31
	v_lshl_add_u64 v[6:7], s[20:21], 2, v[2:3]
	v_add_u32_e32 v17, 2, v4
	v_mad_i64_i32 v[18:19], s[36:37], v17, s3, v[6:7]
	v_add_u32_e32 v17, 4, v4
	v_mad_i64_i32 v[20:21], s[36:37], v17, s3, v[6:7]
	v_add_u32_e32 v17, 6, v4
	v_mad_i64_i32 v[22:23], s[36:37], v17, s3, v[6:7]
	v_add_u32_e32 v17, 8, v4
	v_mad_i64_i32 v[24:25], s[36:37], v17, s3, v[6:7]
	v_add_u32_e32 v17, 10, v4
	v_mad_i64_i32 v[26:27], s[36:37], v17, s3, v[6:7]
	v_add_u32_e32 v17, 12, v4
	v_mad_i64_i32 v[8:9], s[36:37], v4, s3, v[6:7]
	v_mad_i64_i32 v[28:29], s[36:37], v17, s3, v[6:7]
	v_add_u32_e32 v17, 14, v4
	v_mad_i64_i32 v[30:31], s[36:37], v17, s3, v[6:7]
	global_load_dword v17, v[8:9], off nt
	s_nop 0
	global_load_dword v18, v[18:19], off nt
	s_nop 0
	global_load_dword v19, v[20:21], off nt
	s_nop 0
	global_load_dword v20, v[22:23], off nt
	global_load_dword v21, v[24:25], off nt
	s_nop 0
	global_load_dword v22, v[26:27], off nt
	global_load_dword v23, v[28:29], off nt
	global_load_dword v24, v[30:31], off nt
	v_add_u32_e32 v25, 18, v4
	v_mad_i64_i32 v[26:27], s[36:37], v25, s3, v[6:7]
	v_add_u32_e32 v25, 20, v4
	v_mad_i64_i32 v[28:29], s[36:37], v25, s3, v[6:7]
	v_add_u32_e32 v25, 22, v4
	v_mad_i64_i32 v[30:31], s[36:37], v25, s3, v[6:7]
	v_add_u32_e32 v25, 24, v4
	v_mad_i64_i32 v[32:33], s[36:37], v25, s3, v[6:7]
	v_add_u32_e32 v25, 26, v4
	v_add_u32_e32 v8, 16, v4
	v_mad_i64_i32 v[34:35], s[36:37], v25, s3, v[6:7]
	v_add_u32_e32 v25, 28, v4
	v_mad_i64_i32 v[8:9], s[36:37], v8, s3, v[6:7]
	v_mad_i64_i32 v[36:37], s[36:37], v25, s3, v[6:7]
	v_add_u32_e32 v25, 30, v4
	v_mad_i64_i32 v[38:39], s[36:37], v25, s3, v[6:7]
	global_load_dword v25, v[8:9], off nt
	s_nop 0
	global_load_dword v26, v[26:27], off nt
	s_nop 0
	global_load_dword v27, v[28:29], off nt
	s_nop 0
	global_load_dword v28, v[30:31], off nt
	global_load_dword v29, v[32:33], off nt
	s_nop 0
	global_load_dword v30, v[34:35], off nt
	global_load_dword v31, v[36:37], off nt
	global_load_dword v32, v[38:39], off nt
	v_add_u32_e32 v33, 34, v4
	v_mad_i64_i32 v[34:35], s[36:37], v33, s3, v[6:7]
	v_add_u32_e32 v33, 36, v4
	v_mad_i64_i32 v[36:37], s[36:37], v33, s3, v[6:7]
	v_add_u32_e32 v33, 38, v4
	v_mad_i64_i32 v[42:43], s[36:37], v33, s3, v[6:7]
	v_add_u32_e32 v33, 40, v4
	v_mad_i64_i32 v[44:45], s[36:37], v33, s3, v[6:7]
	v_add_u32_e32 v33, 42, v4
	v_mad_i64_i32 v[46:47], s[36:37], v33, s3, v[6:7]
	v_add_u32_e32 v33, 44, v4
	v_add_u32_e32 v8, 32, v4
	v_mad_i64_i32 v[48:49], s[36:37], v33, s3, v[6:7]
	v_add_u32_e32 v33, 46, v4
	v_mad_i64_i32 v[8:9], s[36:37], v8, s3, v[6:7]
	v_mad_i64_i32 v[50:51], s[36:37], v33, s3, v[6:7]
	v_add_u32_e32 v33, 50, v4
	global_load_dword v38, v[8:9], off nt
	global_load_dword v39, v[34:35], off nt
	global_load_dword v40, v[36:37], off nt
	global_load_dword v41, v[42:43], off nt
	s_nop 0
	global_load_dword v42, v[44:45], off nt
	global_load_dword v43, v[46:47], off nt
	s_nop 0
	global_load_dword v44, v[48:49], off nt
	global_load_dword v47, v[50:51], off nt
	v_mad_i64_i32 v[34:35], s[36:37], v33, s3, v[6:7]
	v_add_u32_e32 v33, 52, v4
	v_mad_i64_i32 v[36:37], s[36:37], v33, s3, v[6:7]
	v_add_u32_e32 v33, 54, v4
	v_mad_i64_i32 v[48:49], s[36:37], v33, s3, v[6:7]
	v_add_u32_e32 v33, 56, v4
	v_mad_i64_i32 v[50:51], s[36:37], v33, s3, v[6:7]
	v_add_u32_e32 v33, 58, v4
	v_ashrrev_i32_e32 v5, 31, v4
	v_add_u32_e32 v8, 48, v4
	v_mad_i64_i32 v[52:53], s[36:37], v33, s3, v[6:7]
	v_add_u32_e32 v33, 60, v4
	v_mad_i64_i32 v[8:9], s[36:37], v8, s3, v[6:7]
	v_mad_i64_i32 v[54:55], s[36:37], v33, s3, v[6:7]
	v_add_u32_e32 v33, 62, v4
	v_lshlrev_b64 v[4:5], 2, v[4:5]
	v_mad_i64_i32 v[6:7], s[36:37], v33, s3, v[6:7]
	global_load_dword v115, v[8:9], off nt
	global_load_dword v116, v[34:35], off nt
	global_load_dword v117, v[36:37], off nt
	global_load_dword v118, v[48:49], off nt
	global_load_dword v119, v[50:51], off nt
	global_load_dword v120, v[52:53], off nt
	global_load_dword v121, v[54:55], off nt
	global_load_dword v122, v[6:7], off nt
	v_lshl_add_u64 v[34:35], s[24:25], 0, v[4:5]
	v_add_co_u32_e32 v36, vcc, s26, v34
	v_lshl_add_u64 v[8:9], v[34:35], 0, s[0:1]
	s_nop 0
	v_addc_co_u32_e32 v37, vcc, 0, v35, vcc
	global_load_dword v123, v[36:37], off offset:-4096
	v_lshl_add_u64 v[6:7], s[78:79], 0, v[4:5]
	v_lshl_add_u64 v[4:5], v[34:35], 0, s[14:15]
	global_load_dword v34, v[36:37], off
	global_load_dword v33, v[6:7], off
	global_load_dword v35, v[6:7], off offset:8
	s_nop 0
	global_load_dword v36, v[6:7], off offset:16
	global_load_dword v37, v[6:7], off offset:24
	global_load_dword v45, v[6:7], off offset:32
	global_load_dword v46, v[6:7], off offset:40
	global_load_dword v48, v[6:7], off offset:48
	global_load_dword v49, v[6:7], off offset:56
	global_load_dword v124, v[8:9], off offset:8
	global_load_dword v125, v[8:9], off offset:16
	global_load_dword v126, v[8:9], off offset:24
	global_load_dword v127, v[8:9], off offset:32
	global_load_dword v128, v[8:9], off offset:40
	global_load_dword v129, v[8:9], off offset:48
	global_load_dword v130, v[8:9], off offset:56
	global_load_dword v131, v[8:9], off offset:64
; template <bool SCALED> __device__ __forceinline__ void transpose_item_t(const float* W, int K, int N, bf16* WT, int mode, LAS float* scr, int item, int lane, const float* gvec, const float* scv, const float* shv, float* biasp) {
;     ...
;     for (int i = 0; i < 32; ++i) tv[i] = W[(size_t)(k0 + 2 * i + (lane >> 5)) * N + n0 + (lane & 31)];
;     if (mode == 1) {
;         const float fsc = n0 < DFF ? 1.4426950408889634f : 0.6931471805599453f;
; #pragma unroll
;         for (int i = 0; i < 32; ++i) tv[i] *= fsc;
;     }
;     if (SCALED) {
;         float part = 0.f;
; #pragma unroll
;         for (int i = 0; i < 32; ++i) { const int k = k0 + 2 * i + (lane >> 5); part += tv[i] * shv[k]; tv[i] *= gvec[k] * (1.0f + scv[k]); }
;         part += __shfl_xor(part, 32);
	global_load_dword v58, v[4:5], off offset:8
	global_load_dword v55, v[4:5], off offset:16
	global_load_dword v54, v[4:5], off offset:24
	global_load_dword v53, v[4:5], off offset:32
	global_load_dword v52, v[4:5], off offset:40
	global_load_dword v51, v[4:5], off offset:48
	global_load_dword v50, v[4:5], off offset:56
	global_load_dword v57, v[4:5], off offset:64
	global_load_dword v56, v[6:7], off offset:64
	global_load_dword v59, v[6:7], off offset:72
	global_load_dword v60, v[6:7], off offset:80
	global_load_dword v61, v[6:7], off offset:88
	global_load_dword v62, v[6:7], off offset:96
	global_load_dword v63, v[6:7], off offset:104
	global_load_dword v64, v[6:7], off offset:112
	global_load_dword v65, v[6:7], off offset:120
	global_load_dword v132, v[8:9], off offset:72
	global_load_dword v133, v[8:9], off offset:80
	global_load_dword v134, v[8:9], off offset:88
	global_load_dword v135, v[8:9], off offset:96
	global_load_dword v136, v[8:9], off offset:104
	global_load_dword v137, v[8:9], off offset:112
	global_load_dword v138, v[8:9], off offset:120
	global_load_dword v139, v[8:9], off offset:128
	global_load_dword v74, v[4:5], off offset:72
	global_load_dword v71, v[4:5], off offset:80
	global_load_dword v70, v[4:5], off offset:88
	global_load_dword v69, v[4:5], off offset:96
	global_load_dword v68, v[4:5], off offset:104
	global_load_dword v67, v[4:5], off offset:112
	global_load_dword v66, v[4:5], off offset:120
	global_load_dword v73, v[4:5], off offset:128
	global_load_dword v72, v[6:7], off offset:128
	global_load_dword v75, v[6:7], off offset:136
	global_load_dword v76, v[6:7], off offset:144
	global_load_dword v77, v[6:7], off offset:152
	global_load_dword v78, v[6:7], off offset:160
	global_load_dword v79, v[6:7], off offset:168
	global_load_dword v80, v[6:7], off offset:176
	global_load_dword v81, v[6:7], off offset:184
	global_load_dword v140, v[8:9], off offset:136
	global_load_dword v141, v[8:9], off offset:144
	global_load_dword v142, v[8:9], off offset:152
	global_load_dword v143, v[8:9], off offset:160
	global_load_dword v144, v[8:9], off offset:168
	global_load_dword v145, v[8:9], off offset:176
	global_load_dword v146, v[8:9], off offset:184
	global_load_dword v147, v[8:9], off offset:192
	global_load_dword v89, v[4:5], off offset:136
	global_load_dword v88, v[4:5], off offset:144
	global_load_dword v87, v[4:5], off offset:152
	global_load_dword v86, v[4:5], off offset:160
	global_load_dword v85, v[4:5], off offset:168
	global_load_dword v84, v[4:5], off offset:176
	global_load_dword v82, v[4:5], off offset:184
	global_load_dword v83, v[4:5], off offset:192
	global_load_dword v148, v[8:9], off offset:200
	global_load_dword v149, v[8:9], off offset:208
	global_load_dword v150, v[8:9], off offset:216
	global_load_dword v151, v[8:9], off offset:224
	global_load_dword v152, v[8:9], off offset:232
	global_load_dword v153, v[8:9], off offset:240
	global_load_dword v154, v[8:9], off offset:248
	global_load_dword v94, v[6:7], off offset:192
	global_load_dword v93, v[6:7], off offset:200
	global_load_dword v92, v[6:7], off offset:208
	global_load_dword v91, v[6:7], off offset:216
	global_load_dword v90, v[6:7], off offset:224
	global_load_dword v9, v[6:7], off offset:232
	global_load_dword v8, v[6:7], off offset:240
	global_load_dword v99, v[6:7], off offset:248
	global_load_dword v98, v[4:5], off offset:200
	global_load_dword v97, v[4:5], off offset:208
	global_load_dword v96, v[4:5], off offset:216
	global_load_dword v95, v[4:5], off offset:224
	s_nop 0
	global_load_dword v7, v[4:5], off offset:232
	global_load_dword v6, v[4:5], off offset:240
	global_load_dword v111, v[4:5], off offset:248
	s_add_i32 s35, s35, s20
	s_lshl_b32 s21, s35, 1
	s_and_b32 s20, s20, 0x60
	s_and_b32 s21, s21, 0xffffff00
	s_or_b32 s20, s34, s20
	s_or_b32 s20, s20, s21
	s_cmpk_lt_i32 s31, 0x58
	s_cselect_b64 vcc, -1, 0
	v_cndmask_b32_e32 v155, v14, v15, vcc
	s_waitcnt vmcnt(62)
	v_mul_f32_e32 v114, v155, v17
	v_mul_f32_e32 v113, v155, v18
	v_mul_f32_e32 v112, v155, v19
	v_mul_f32_e32 v110, v155, v20
	v_mul_f32_e32 v109, v155, v21
	v_mul_f32_e32 v101, v155, v29
	v_mul_f32_e32 v108, v155, v22
	v_mul_f32_e32 v107, v155, v23
	v_mul_f32_e32 v106, v155, v24
	v_mul_f32_e32 v105, v155, v25
	v_mul_f32_e32 v104, v155, v26
	v_mul_f32_e32 v103, v155, v27
	v_mul_f32_e32 v102, v155, v28
	v_mul_f32_e32 v100, v155, v30
	v_mul_f32_e32 v31, v155, v31
	v_mul_f32_e32 v30, v155, v32
	v_mul_f32_e32 v29, v155, v38
	v_mul_f32_e32 v28, v155, v39
	v_mul_f32_e32 v27, v155, v40
	v_mul_f32_e32 v26, v155, v41
	v_mul_f32_e32 v25, v155, v42
	v_mul_f32_e32 v24, v155, v43
	v_mul_f32_e32 v23, v155, v44
	v_mul_f32_e32 v22, v155, v47
	v_mul_f32_e32 v21, v155, v115
	v_mul_f32_e32 v20, v155, v116
	v_mul_f32_e32 v19, v155, v117
	v_mul_f32_e32 v18, v155, v118
	v_mul_f32_e32 v17, v155, v119
	v_mul_f32_e32 v5, v155, v120
	v_mul_f32_e32 v4, v155, v121
	v_mul_f32_e32 v32, v155, v122
	v_fma_f32 v38, v114, v123, 0
	v_fmac_f32_e32 v38, v113, v124
	v_fmac_f32_e32 v38, v112, v125
	v_fmac_f32_e32 v38, v110, v126
	v_fmac_f32_e32 v38, v109, v127
	v_fmac_f32_e32 v38, v108, v128
	v_fmac_f32_e32 v38, v107, v129
	v_fmac_f32_e32 v38, v106, v130
	v_fmac_f32_e32 v38, v105, v131
	s_waitcnt vmcnt(61)
	v_fmac_f32_e32 v38, v104, v132
	s_waitcnt vmcnt(60)
	v_fmac_f32_e32 v38, v103, v133
	s_waitcnt vmcnt(59)
	v_fmac_f32_e32 v38, v102, v134
	s_waitcnt vmcnt(58)
	v_fmac_f32_e32 v38, v101, v135
	s_waitcnt vmcnt(57)
	v_fmac_f32_e32 v38, v100, v136
	s_waitcnt vmcnt(56)
	v_fmac_f32_e32 v38, v31, v137
	s_waitcnt vmcnt(55)
	v_fmac_f32_e32 v38, v30, v138
	s_waitcnt vmcnt(54)
	v_fmac_f32_e32 v38, v29, v139
	s_waitcnt vmcnt(37)
	v_fmac_f32_e32 v38, v28, v140
	s_waitcnt vmcnt(36)
	v_fmac_f32_e32 v38, v27, v141
	s_waitcnt vmcnt(35)
	v_fmac_f32_e32 v38, v26, v142
	s_waitcnt vmcnt(34)
	v_fmac_f32_e32 v38, v25, v143
	s_waitcnt vmcnt(33)
	v_fmac_f32_e32 v38, v24, v144
	s_waitcnt vmcnt(32)
	v_fmac_f32_e32 v38, v23, v145
	s_waitcnt vmcnt(31)
	v_fmac_f32_e32 v38, v22, v146
	s_waitcnt vmcnt(30)
	v_fmac_f32_e32 v38, v21, v147
	s_waitcnt vmcnt(21)
	v_fmac_f32_e32 v38, v20, v148
	s_waitcnt vmcnt(20)
	v_fmac_f32_e32 v38, v19, v149
	s_waitcnt vmcnt(19)
	v_fmac_f32_e32 v38, v18, v150
	s_waitcnt vmcnt(18)
	v_fmac_f32_e32 v38, v17, v151
	s_waitcnt vmcnt(17)
	v_fmac_f32_e32 v38, v5, v152
	s_waitcnt vmcnt(16)
	v_fmac_f32_e32 v38, v4, v153
	s_waitcnt vmcnt(15)
	v_fmac_f32_e32 v38, v32, v154
	ds_bpermute_b32 v39, v11, v38
	s_and_saveexec_b64 s[24:25], s[4:5]
	s_cbranch_execz .LBB0_127
; template <bool SCALED> __device__ __forceinline__ void transpose_item_t(const float* W, int K, int N, bf16* WT, int mode, LAS float* scr, int item, int lane, const float* gvec, const float* scv, const float* shv, float* biasp) {
;     ...
;         part += __shfl_xor(part, 32);
;         if (lane < 32) biasp[(size_t)kb * NBIAS + d0 + lane] = part;
	s_and_b64 s[34:35], s[18:19], exec
	s_cselect_b32 s21, 0x98000, 0
	s_add_u32 s31, s6, s21
	s_addc_u32 s34, s7, 0
	s_ashr_i32 s21, s20, 31
	s_mul_hi_i32 s35, s17, 0x9800
	s_mul_i32 s17, s17, 0x9800
	s_add_u32 s17, s31, s17
	s_addc_u32 s31, s34, s35
	s_lshl_b64 s[34:35], s[20:21], 2
	s_add_u32 s34, s17, s34
	s_addc_u32 s35, s31, s35
	s_waitcnt lgkmcnt(0)
	v_add_f32_e32 v40, v38, v39
	v_lshl_add_u64 v[38:39], v[160:161], 2, s[34:35]
	v_add_co_u32_e32 v38, vcc, 0x4000, v38
	s_nop 1
	v_addc_co_u32_e32 v39, vcc, 0, v39, vcc
	global_store_dword v[38:39], v40, off
	s_branch .LBB0_127

; #define LAS __attribute__((address_space(3)))
; __device__ __forceinline__ int dst_row0(int mode, int n0) {
;     if (mode == 1) { const int hb = n0 >= DFF ? 1 : 0, j = n0 - hb * DFF; return 256 * (j >> 7) + 128 * hb + (j & 127); }
;     if (mode == 2 && n0 < 1024) { const int pn = n0 >> 8, c = n0 & 255, hh = c >> 6, e = c & 63; return 256 * pn + 128 * (e >> 5) + 32 * hh + (e & 31); }
;     return n0;
; }
; template <bool SCALED> __device__ __forceinline__ void transpose_item_t(const float* W, int K, int N, bf16* WT, int mode, LAS float* scr, int item, int lane, const float* gvec, const float* scv, const float* shv, float* biasp) {
;     const int nblk = N / 32, kb = item / nblk, nb = item % nblk, k0 = 64 * kb, n0 = 32 * nb, d0 = dst_row0(mode, n0);
;     float tv[32];
; #pragma unroll
;     for (int i = 0; i < 32; ++i) tv[i] = W[(size_t)(k0 + 2 * i + (lane >> 5)) * N + n0 + (lane & 31)];
;     if (mode == 1) {
;         const float fsc = n0 < DFF ? 1.4426950408889634f : 0.6931471805599453f;
; #pragma unroll
;         for (int i = 0; i < 32; ++i) tv[i] *= fsc;
;     }
;     if (SCALED) {
;         float part = 0.f;
; #pragma unroll
;         for (int i = 0; i < 32; ++i) { const int k = k0 + 2 * i + (lane >> 5); part += tv[i] * shv[k]; tv[i] *= gvec[k] * (1.0f + scv[k]); }
; __global__ void __launch_bounds__(512, 2) hybrid_fwd(Args args) {
;     ...
;             for (int it = (blk - hb) * 8 + wave; it < 2 * I_IN; it += (G - hb) * 8) { const int bb = it >= I_IN ? 1 : 0; const float* mb = mod + bb * NADA;
;                 transpose_item_t<true>(w_in, DM, NIN, WIN + (size_t)bb * NIN * DM, 2, scr, it - bb * I_IN, lane, g_mix, mb + 4 * DM, mb + 3 * DM, BIASP + (size_t)bb * 16 * NBIAS); }
.LBB0_205:
	s_cmpk_gt_i32 s3, 0x7ff
	s_cselect_b64 s[16:17], -1, 0
	s_and_b64 s[0:1], s[16:17], exec
	s_cselect_b32 s0, 0x9000, 0
	s_cselect_b32 s1, 0xfffff800, 0
	s_add_u32 s18, s22, s0
	s_addc_u32 s19, s23, 0
	s_add_i32 s0, s1, s3
	s_ashr_i32 s1, s0, 31
	s_lshr_b32 s1, s1, 25
	s_add_i32 s1, s0, s1
	s_ashr_i32 s15, s1, 7
	s_and_b32 s1, s1, 0xffffff80
	s_sub_i32 s1, s0, s1
	s_lshl_b32 s0, s1, 5
	s_lshl_b32 s12, s1, 7
	s_and_b32 s12, s12, 0x80
	s_lshl_b32 s13, s1, 4
	s_and_b32 s78, s0, 0xffffff00
	s_and_b32 s13, s13, 0x60
	s_or_b32 s12, s78, s12
	s_lshl_b32 s14, s15, 6
	s_or_b32 s12, s12, s13
	s_cmp_lt_i32 s1, 32
	v_add_u32_e32 v4, s14, v10
	s_cselect_b32 s12, s12, s0
	s_ashr_i32 s1, s0, 31
	v_ashrrev_i32_e32 v5, 31, v4
	v_lshl_add_u64 v[6:7], s[0:1], 2, v[2:3]
	v_lshlrev_b64 v[8:9], 14, v[4:5]
	v_lshl_add_u64 v[6:7], v[6:7], 0, v[8:9]
	s_mov_b32 s0, 0x8000
	v_add_co_u32_e64 v8, s[0:1], s0, v6
	v_lshlrev_b64 v[4:5], 2, v[4:5]
	s_nop 0
	v_addc_co_u32_e64 v9, s[0:1], 0, v7, s[0:1]
	s_mov_b32 s0, 0x10000
	s_nop 0
	v_add_co_u32_e64 v16, s[0:1], s0, v6
	s_nop 1
	v_addc_co_u32_e64 v17, s[0:1], 0, v7, s[0:1]
	s_mov_b32 s0, 0x18000
	s_nop 0
	v_add_co_u32_e64 v22, s[0:1], s0, v6
	s_nop 1
	v_addc_co_u32_e64 v23, s[0:1], 0, v7, s[0:1]
	v_add_co_u32_e64 v24, s[0:1], s21, v6
	s_nop 1
	v_addc_co_u32_e64 v25, s[0:1], 0, v7, s[0:1]
	v_add_co_u32_e64 v26, s[0:1], s34, v6
	s_nop 1
	v_addc_co_u32_e64 v27, s[0:1], 0, v7, s[0:1]
	v_add_co_u32_e64 v28, s[0:1], s35, v6
	s_nop 1
	v_addc_co_u32_e64 v29, s[0:1], 0, v7, s[0:1]
	v_add_co_u32_e64 v30, s[0:1], s36, v6
	s_nop 1
	v_addc_co_u32_e64 v31, s[0:1], 0, v7, s[0:1]
	global_load_dword v21, v[6:7], off
	global_load_dword v20, v[8:9], off nt
	global_load_dword v19, v[16:17], off nt
	global_load_dword v18, v[22:23], off nt
	s_nop 0
	global_load_dword v17, v[24:25], off nt
	global_load_dword v16, v[26:27], off nt
	global_load_dword v15, v[28:29], off nt
	global_load_dword v22, v[30:31], off nt
	v_add_co_u32_e64 v8, s[0:1], s37, v6
	s_nop 1
	v_addc_co_u32_e64 v9, s[0:1], 0, v7, s[0:1]
	v_add_co_u32_e64 v24, s[0:1], s38, v6
	s_nop 1
	v_addc_co_u32_e64 v25, s[0:1], 0, v7, s[0:1]
	v_add_co_u32_e64 v26, s[0:1], s39, v6
	s_nop 1
	v_addc_co_u32_e64 v27, s[0:1], 0, v7, s[0:1]
	v_add_co_u32_e64 v30, s[0:1], s40, v6
	s_nop 1
	v_addc_co_u32_e64 v31, s[0:1], 0, v7, s[0:1]
	v_add_co_u32_e64 v32, s[0:1], s41, v6
	s_nop 1
	v_addc_co_u32_e64 v33, s[0:1], 0, v7, s[0:1]
	v_add_co_u32_e64 v34, s[0:1], s44, v6
	s_nop 1
	v_addc_co_u32_e64 v35, s[0:1], 0, v7, s[0:1]
	v_add_co_u32_e64 v36, s[0:1], s45, v6
	s_nop 1
	v_addc_co_u32_e64 v37, s[0:1], 0, v7, s[0:1]
	v_add_co_u32_e64 v38, s[0:1], s52, v6
	s_nop 1
	v_addc_co_u32_e64 v39, s[0:1], 0, v7, s[0:1]
	global_load_dword v29, v[8:9], off nt
	global_load_dword v28, v[24:25], off nt
	s_nop 0
	global_load_dword v27, v[26:27], off nt
	s_nop 0
	global_load_dword v26, v[30:31], off nt
	global_load_dword v25, v[32:33], off nt
	global_load_dword v24, v[34:35], off nt
	global_load_dword v23, v[36:37], off nt
	s_nop 0
	global_load_dword v30, v[38:39], off nt
	v_add_co_u32_e64 v8, s[0:1], s53, v6
	s_nop 1
	v_addc_co_u32_e64 v9, s[0:1], 0, v7, s[0:1]
	v_add_co_u32_e64 v32, s[0:1], s54, v6
	s_nop 1
	v_addc_co_u32_e64 v33, s[0:1], 0, v7, s[0:1]
	v_add_co_u32_e64 v34, s[0:1], s55, v6
	s_nop 1
	v_addc_co_u32_e64 v35, s[0:1], 0, v7, s[0:1]
	v_add_co_u32_e64 v38, s[0:1], s56, v6
	s_nop 1
	v_addc_co_u32_e64 v39, s[0:1], 0, v7, s[0:1]
	v_add_co_u32_e64 v40, s[0:1], s57, v6
	s_nop 1
	v_addc_co_u32_e64 v41, s[0:1], 0, v7, s[0:1]
	v_add_co_u32_e64 v42, s[0:1], s58, v6
	s_nop 1
	v_addc_co_u32_e64 v43, s[0:1], 0, v7, s[0:1]
	v_add_co_u32_e64 v44, s[0:1], s59, v6
	s_nop 1
	v_addc_co_u32_e64 v45, s[0:1], 0, v7, s[0:1]
	v_add_co_u32_e64 v46, s[0:1], s62, v6
	s_nop 1
	v_addc_co_u32_e64 v47, s[0:1], 0, v7, s[0:1]
	global_load_dword v37, v[8:9], off nt
	global_load_dword v36, v[32:33], off nt
	s_nop 0
	global_load_dword v35, v[34:35], off nt
	s_nop 0
	global_load_dword v34, v[38:39], off nt
	global_load_dword v33, v[40:41], off nt
	global_load_dword v32, v[42:43], off nt
	global_load_dword v31, v[44:45], off nt
	s_nop 0
	global_load_dword v38, v[46:47], off nt
	v_add_co_u32_e64 v8, s[0:1], s63, v6
	s_nop 1
	v_addc_co_u32_e64 v9, s[0:1], 0, v7, s[0:1]
	v_add_co_u32_e64 v40, s[0:1], s64, v6
	s_nop 1
	v_addc_co_u32_e64 v41, s[0:1], 0, v7, s[0:1]
	v_add_co_u32_e64 v42, s[0:1], s65, v6
	s_nop 1
	v_addc_co_u32_e64 v43, s[0:1], 0, v7, s[0:1]
	v_add_co_u32_e64 v46, s[0:1], s66, v6
	s_nop 1
	v_addc_co_u32_e64 v47, s[0:1], 0, v7, s[0:1]
	v_add_co_u32_e64 v48, s[0:1], s67, v6
	s_nop 1
	v_addc_co_u32_e64 v49, s[0:1], 0, v7, s[0:1]
	v_add_co_u32_e64 v50, s[0:1], s70, v6
	s_nop 1
	v_addc_co_u32_e64 v51, s[0:1], 0, v7, s[0:1]
	v_add_co_u32_e64 v52, s[0:1], s71, v6
	s_nop 1
	v_addc_co_u32_e64 v53, s[0:1], 0, v7, s[0:1]
	v_add_co_u32_e64 v6, s[0:1], s72, v6
	s_nop 1
	v_addc_co_u32_e64 v7, s[0:1], 0, v7, s[0:1]
	global_load_dword v45, v[8:9], off nt
	global_load_dword v44, v[40:41], off nt
	s_nop 0
	global_load_dword v43, v[42:43], off nt
	s_nop 0
	global_load_dword v42, v[46:47], off nt
	global_load_dword v41, v[48:49], off nt
	global_load_dword v40, v[50:51], off nt
	global_load_dword v39, v[52:53], off nt
	s_nop 0
	global_load_dword v46, v[6:7], off nt
	v_lshl_add_u64 v[48:49], s[18:19], 0, v[4:5]
	v_add_co_u32_e64 v50, s[0:1], s73, v48
	v_lshl_add_u64 v[8:9], v[48:49], 0, s[4:5]
	s_nop 0
	v_addc_co_u32_e64 v51, s[0:1], 0, v49, s[0:1]
	global_load_dword v69, v[50:51], off offset:-4096 nt
	v_lshl_add_u64 v[6:7], s[74:75], 0, v[4:5]
	v_lshl_add_u64 v[4:5], v[48:49], 0, s[8:9]
	global_load_dword v48, v[50:51], off nt
; template <bool SCALED> __device__ __forceinline__ void transpose_item_t(const float* W, int K, int N, bf16* WT, int mode, LAS float* scr, int item, int lane, const float* gvec, const float* scv, const float* shv, float* biasp) {
;     ...
;     if (SCALED) {
;         float part = 0.f;
; #pragma unroll
;         for (int i = 0; i < 32; ++i) { const int k = k0 + 2 * i + (lane >> 5); part += tv[i] * shv[k]; tv[i] *= gvec[k] * (1.0f + scv[k]); }
;         part += __shfl_xor(part, 32);
;         if (lane < 32) biasp[(size_t)kb * NBIAS + d0 + lane] = part;
	global_load_dword v47, v[6:7], off
	global_load_dword v49, v[6:7], off offset:8
	s_nop 0
	global_load_dword v50, v[6:7], off offset:16
	global_load_dword v51, v[6:7], off offset:24
	global_load_dword v52, v[6:7], off offset:32
	global_load_dword v53, v[6:7], off offset:40
	global_load_dword v54, v[6:7], off offset:48
	global_load_dword v55, v[6:7], off offset:56
	global_load_dword v107, v[8:9], off offset:8
	global_load_dword v108, v[8:9], off offset:16
	global_load_dword v109, v[8:9], off offset:24
	global_load_dword v110, v[8:9], off offset:32
	global_load_dword v111, v[8:9], off offset:40
	global_load_dword v112, v[8:9], off offset:48
	global_load_dword v113, v[8:9], off offset:56
	global_load_dword v114, v[8:9], off offset:64
	global_load_dword v62, v[4:5], off offset:8
	global_load_dword v61, v[4:5], off offset:16
	global_load_dword v60, v[4:5], off offset:24
	global_load_dword v59, v[4:5], off offset:32
	global_load_dword v58, v[4:5], off offset:40
	global_load_dword v57, v[4:5], off offset:48
	global_load_dword v56, v[4:5], off offset:56
	global_load_dword v64, v[4:5], off offset:64
	global_load_dword v63, v[6:7], off offset:64
	global_load_dword v65, v[6:7], off offset:72
	global_load_dword v66, v[6:7], off offset:80
	global_load_dword v67, v[6:7], off offset:88
	global_load_dword v68, v[6:7], off offset:96
	global_load_dword v70, v[6:7], off offset:104
	global_load_dword v71, v[6:7], off offset:112
	global_load_dword v72, v[6:7], off offset:120
	global_load_dword v115, v[8:9], off offset:72
	global_load_dword v116, v[8:9], off offset:80
	global_load_dword v117, v[8:9], off offset:88
	global_load_dword v118, v[8:9], off offset:96
	global_load_dword v119, v[8:9], off offset:104
	global_load_dword v120, v[8:9], off offset:112
	global_load_dword v121, v[8:9], off offset:120
	global_load_dword v122, v[8:9], off offset:128
	global_load_dword v79, v[4:5], off offset:72
	global_load_dword v78, v[4:5], off offset:80
	global_load_dword v77, v[4:5], off offset:88
	global_load_dword v76, v[4:5], off offset:96
	global_load_dword v75, v[4:5], off offset:104
	global_load_dword v74, v[4:5], off offset:112
	global_load_dword v73, v[4:5], off offset:120
	global_load_dword v81, v[4:5], off offset:128
	global_load_dword v80, v[6:7], off offset:128
	global_load_dword v82, v[6:7], off offset:136
	global_load_dword v83, v[6:7], off offset:144
	global_load_dword v84, v[6:7], off offset:152
	global_load_dword v85, v[6:7], off offset:160
	global_load_dword v86, v[6:7], off offset:168
	global_load_dword v87, v[6:7], off offset:176
	global_load_dword v88, v[6:7], off offset:184
	global_load_dword v123, v[8:9], off offset:136
	global_load_dword v124, v[8:9], off offset:144
	global_load_dword v125, v[8:9], off offset:152
	global_load_dword v126, v[8:9], off offset:160
	global_load_dword v127, v[8:9], off offset:168
	global_load_dword v128, v[8:9], off offset:176
	global_load_dword v129, v[8:9], off offset:184
	global_load_dword v130, v[8:9], off offset:192
	global_load_dword v95, v[4:5], off offset:136
	global_load_dword v94, v[4:5], off offset:144
	global_load_dword v93, v[4:5], off offset:152
	global_load_dword v92, v[4:5], off offset:160
	global_load_dword v91, v[4:5], off offset:168
	global_load_dword v90, v[4:5], off offset:176
	global_load_dword v89, v[4:5], off offset:184
	global_load_dword v96, v[4:5], off offset:192
	global_load_dword v131, v[8:9], off offset:200
	global_load_dword v132, v[8:9], off offset:208
	global_load_dword v133, v[8:9], off offset:216
	global_load_dword v134, v[8:9], off offset:224
	global_load_dword v135, v[8:9], off offset:232
	global_load_dword v136, v[8:9], off offset:240
	global_load_dword v137, v[8:9], off offset:248
	global_load_dword v101, v[6:7], off offset:192
	global_load_dword v100, v[6:7], off offset:200
	global_load_dword v99, v[6:7], off offset:208
	global_load_dword v98, v[6:7], off offset:216
	global_load_dword v97, v[6:7], off offset:224
	global_load_dword v9, v[6:7], off offset:232
	global_load_dword v8, v[6:7], off offset:240
	global_load_dword v106, v[6:7], off offset:248
	global_load_dword v105, v[4:5], off offset:200
	global_load_dword v104, v[4:5], off offset:208
	global_load_dword v103, v[4:5], off offset:216
	global_load_dword v102, v[4:5], off offset:224
	s_nop 0
	global_load_dword v7, v[4:5], off offset:232
	global_load_dword v6, v[4:5], off offset:240
	s_nop 0
	global_load_dword v4, v[4:5], off offset:248
	s_waitcnt vmcnt(0)
	v_fma_f32 v5, v21, v69, 0
	v_fmac_f32_e32 v5, v20, v107
	v_fmac_f32_e32 v5, v19, v108
	v_fmac_f32_e32 v5, v18, v109
	v_fmac_f32_e32 v5, v17, v110
	v_fmac_f32_e32 v5, v16, v111
	v_fmac_f32_e32 v5, v15, v112
	v_fmac_f32_e32 v5, v22, v113
	v_fmac_f32_e32 v5, v29, v114
	v_fmac_f32_e32 v5, v28, v115
	v_fmac_f32_e32 v5, v27, v116
	v_fmac_f32_e32 v5, v26, v117
	v_fmac_f32_e32 v5, v25, v118
	v_fmac_f32_e32 v5, v24, v119
	v_fmac_f32_e32 v5, v23, v120
	v_fmac_f32_e32 v5, v30, v121
	v_fmac_f32_e32 v5, v37, v122
	v_fmac_f32_e32 v5, v36, v123
	v_fmac_f32_e32 v5, v35, v124
	v_fmac_f32_e32 v5, v34, v125
	v_fmac_f32_e32 v5, v33, v126
	v_fmac_f32_e32 v5, v32, v127
	v_fmac_f32_e32 v5, v31, v128
	v_fmac_f32_e32 v5, v38, v129
	v_fmac_f32_e32 v5, v45, v130
	v_fmac_f32_e32 v5, v44, v131
	v_fmac_f32_e32 v5, v43, v132
	v_fmac_f32_e32 v5, v42, v133
	v_fmac_f32_e32 v5, v41, v134
	v_fmac_f32_e32 v5, v40, v135
	v_fmac_f32_e32 v5, v39, v136
	v_fmac_f32_e32 v5, v46, v137
	ds_bpermute_b32 v69, v11, v5
	s_and_saveexec_b64 s[0:1], vcc
	s_cbranch_execz .LBB0_204
	s_and_b64 s[18:19], s[16:17], exec
	s_cselect_b32 s13, 0x98000, 0
	s_add_u32 s18, s6, s13
	s_addc_u32 s19, s7, 0
	s_ashr_i32 s13, s12, 31
	s_mul_hi_i32 s78, s15, 0x9800
	s_mul_i32 s15, s15, 0x9800
	s_add_u32 s15, s18, s15
	s_addc_u32 s78, s19, s78
	s_lshl_b64 s[18:19], s[12:13], 2
	s_add_u32 s18, s15, s18
	s_addc_u32 s19, s78, s19
	s_waitcnt lgkmcnt(0)
	v_add_f32_e32 v5, v5, v69
	v_lshl_add_u64 v[108:109], v[160:161], 2, s[18:19]
	global_store_dword v[108:109], v5, off
	s_branch .LBB0_204
